# combined: rmsnorm load batching, barrier followers poll top word, scalar f32 adds in attention score init and S5 scan
# speedup vs baseline: 1.0063x; 1.0063x over previous
; #define LAS __attribute__((address_space(3)))
; DI f32x4 mfma16(bf16x8 a, bf16x8 b, f32x4 c) { return __builtin_amdgcn_mfma_f32_16x16x32_bf16(a, b, c, 0, 0, 0); }
; DI void nsa_attn_phase(const int tid0, LAS unsigned char* lds, const P& p, int G, int c) {
;     ...
;                         const bool bsel = nvalid && ((br == 1) || ((sm[qt] >> n) & 1u));
;                         act[h][qt] = nvalid && ((br == 1) || (__ballot(bsel) != 0ull));
;                         pf[h][0][qt] = (bf16x8){0, 0, 0, 0, 0, 0, 0, 0}; pf[h][1][qt] = pf[h][0][qt];
;                         if (act[h][qt]) {
;                             const float sb = bsel ? slope2 * (float)(n * 64 + fq * 4 - tq[qt]) : -1e9f;
;                             f32x4 S[4];
; #pragma unroll
;                             for (int kt = 0; kt < 4; ++kt) { S[kt] = (f32x4){sb + sc16[kt * 4], sb + sc16[kt * 4 + 1], sb + sc16[kt * 4 + 2], sb + sc16[kt * 4 + 3]};
; #pragma unroll
;                                 for (int ks = 0; ks < 2; ++ks) { const bf16x8 kf = *(const LAS bf16x8*)(Kt + (kt * 16 + fr) * 72 + ks * 32 + fq * 8); S[kt] = mfma16(kf, Qf[qt][ks], S[kt]); } }
;                             float ls = 0.f;
;                             if (edge) {
; #pragma unroll
;                                 for (int kt = 0; kt < 4; ++kt)
; #pragma unroll
;                                     for (int j = 0; j < 4; ++j) { const int pos = n * 64 + kt * 16 + fq * 4 + j; const bool valid = (pos <= tq[qt]) && (br == 0 || pos > tq[qt] - 256);
;                                         const float pv = valid ? __builtin_amdgcn_exp2f(S[kt][j]) : 0.f; S[kt][j] = pv; ls += pv; }
;                             } else {
; #pragma unroll
;                                 for (int kt = 0; kt < 4; ++kt)
; #pragma unroll
;                                     for (int j = 0; j < 4; ++j) { const float pv = __builtin_amdgcn_exp2f(S[kt][j]); S[kt][j] = pv; ls += pv; }
;                             }
;                             lrun[qt] += ls;
.LBB0_238:
	s_bitcmp0_b32 s0, 0
	s_cselect_b64 s[8:9], -1, 0
	s_and_b64 s[0:1], s[8:9], exec
	s_cselect_b32 s0, s94, 0
	s_add_i32 s14, s58, -3
	s_add_i32 s15, s41, s58
	s_cmp_le_i32 s14, s44
	s_cselect_b64 s[12:13], -1, 0
	s_cmp_lg_u32 s15, 34
	v_add_u32_e32 v139, s0, v187
	s_cselect_b64 s[0:1], -1, 0
	s_lshl_b32 s16, 1, s14
	s_cmp_gt_i32 s14, s44
	v_add_u32_e32 v138, s19, v190
	s_mov_b64 s[10:11], 0
	s_cbranch_scc1 .LBB0_246
	v_and_b32_e32 v0, s16, v150
	v_cmp_ne_u32_e32 vcc, 0, v0
	s_cbranch_vccz .LBB0_253
	v_add_u32_e32 v0, s19, v97
	v_add_u32_e32 v0, 0xfffff840, v0
	v_cvt_f32_i32_e32 v0, v0
	v_add_u32_e32 v118, v139, v179
	ds_read_b128 v[162:165], v118
	ds_read_b128 v[166:169], v118 offset:64
	ds_read_b128 v[206:209], v118 offset:2304
	ds_read_b128 v[214:217], v118 offset:2368
	ds_read_b128 v[218:221], v118 offset:4608
	ds_read_b128 v[222:225], v118 offset:4672
	ds_read_b128 v[226:229], v118 offset:6912
	ds_read_b128 v[238:241], v118 offset:6976
	s_mov_b64 s[4:5], -1
	v_mul_f32_e32 v0, v186, v0
	v_cndmask_b32_e32 v114, v236, v0, vcc
	v_add_f32_e64 v6, v194, v114
	v_add_f32_e64 v7, v195, v114
	v_add_f32_e64 v4, v192, v114
	v_add_f32_e64 v5, v193, v114
	v_add_f32_e64 v10, v196, v114
	v_add_f32_e64 v11, v197, v114
	v_add_f32_e64 v8, v188, v114
	v_add_f32_e64 v9, v189, v114
	v_add_f32_e64 v14, v200, v114
	v_add_f32_e64 v15, v201, v114
	v_add_f32_e64 v12, v198, v114
	v_add_f32_e64 v13, v199, v114
	v_add_f32_e64 v116, v204, v114
	v_add_f32_e64 v117, v205, v114
	s_waitcnt lgkmcnt(7)
	v_mfma_f32_16x16x32_bf16 v[0:3], v[162:165], v[16:19], v[4:7]
	v_add_f32_e64 v115, v203, v114
	v_add_f32_e64 v114, v202, v114
	s_andn2_b64 vcc, exec, s[0:1]
	s_waitcnt lgkmcnt(6)
	v_mfma_f32_16x16x32_bf16 v[0:3], v[166:169], v[20:23], v[0:3]
	s_nop 7
	v_exp_f32_e32 v0, v0
	s_waitcnt lgkmcnt(5)
	v_mfma_f32_16x16x32_bf16 v[4:7], v[206:209], v[16:19], v[8:11]
	v_exp_f32_e32 v1, v1
	v_exp_f32_e32 v2, v2
	s_waitcnt lgkmcnt(4)
	v_mfma_f32_16x16x32_bf16 v[4:7], v[214:217], v[20:23], v[4:7]
	v_exp_f32_e32 v3, v3
	s_nop 6
	v_exp_f32_e32 v4, v4
	s_waitcnt lgkmcnt(3)
	v_mfma_f32_16x16x32_bf16 v[8:11], v[218:221], v[16:19], v[12:15]
	v_exp_f32_e32 v5, v5
	v_exp_f32_e32 v6, v6
	s_waitcnt lgkmcnt(2)
	v_mfma_f32_16x16x32_bf16 v[8:11], v[222:225], v[20:23], v[8:11]
	v_exp_f32_e32 v7, v7
	s_nop 6
	v_exp_f32_e32 v8, v8
	s_waitcnt lgkmcnt(1)
	v_mfma_f32_16x16x32_bf16 v[12:15], v[226:229], v[16:19], v[114:117]
	v_exp_f32_e32 v9, v9
	v_exp_f32_e32 v10, v10
	s_waitcnt lgkmcnt(0)
	v_mfma_f32_16x16x32_bf16 v[12:15], v[238:241], v[20:23], v[12:15]
	v_exp_f32_e32 v11, v11
	s_nop 6
	v_exp_f32_e32 v12, v12
	v_exp_f32_e32 v13, v13
	v_exp_f32_e32 v14, v14
	v_exp_f32_e32 v15, v15
	v_mov_b32_e32 v114, v238
	s_cbranch_vccnz .LBB0_242
	v_add_f32_e32 v114, 0, v0
	v_add_f32_e32 v114, v1, v114
	v_add_f32_e32 v114, v2, v114
	v_add_f32_e32 v114, v3, v114
	v_add_f32_e32 v114, v114, v4
	v_add_f32_e32 v114, v5, v114
	v_add_f32_e32 v114, v6, v114
	v_add_f32_e32 v114, v7, v114
	v_add_f32_e32 v114, v114, v8
	v_add_f32_e32 v114, v9, v114
	v_add_f32_e32 v114, v10, v114
	v_add_f32_e32 v114, v11, v114
	v_add_f32_e32 v114, v114, v12
	v_add_f32_e32 v114, v13, v114
	v_add_f32_e32 v114, v14, v114
	v_add_f32_e32 v114, v15, v114
	s_mov_b64 s[4:5], 0

; #define LAS __attribute__((address_space(3)))
; DI f32x4 mfma16(bf16x8 a, bf16x8 b, f32x4 c) { return __builtin_amdgcn_mfma_f32_16x16x32_bf16(a, b, c, 0, 0, 0); }
; DI void nsa_attn_phase(const int tid0, LAS unsigned char* lds, const P& p, int G, int c) {
;     ...
;                         const bool bsel = nvalid && ((br == 1) || ((sm[qt] >> n) & 1u));
;                         act[h][qt] = nvalid && ((br == 1) || (__ballot(bsel) != 0ull));
;                         pf[h][0][qt] = (bf16x8){0, 0, 0, 0, 0, 0, 0, 0}; pf[h][1][qt] = pf[h][0][qt];
;                         if (act[h][qt]) {
;                             const float sb = bsel ? slope2 * (float)(n * 64 + fq * 4 - tq[qt]) : -1e9f;
;                             f32x4 S[4];
; #pragma unroll
;                             for (int kt = 0; kt < 4; ++kt) { S[kt] = (f32x4){sb + sc16[kt * 4], sb + sc16[kt * 4 + 1], sb + sc16[kt * 4 + 2], sb + sc16[kt * 4 + 3]};
; #pragma unroll
;                                 for (int ks = 0; ks < 2; ++ks) { const bf16x8 kf = *(const LAS bf16x8*)(Kt + (kt * 16 + fr) * 72 + ks * 32 + fq * 8); S[kt] = mfma16(kf, Qf[qt][ks], S[kt]); } }
;                             float ls = 0.f;
;                             if (edge) {
; #pragma unroll
;                                 for (int kt = 0; kt < 4; ++kt)
; #pragma unroll
;                                     for (int j = 0; j < 4; ++j) { const int pos = n * 64 + kt * 16 + fq * 4 + j; const bool valid = (pos <= tq[qt]) && (br == 0 || pos > tq[qt] - 256);
;                                         const float pv = valid ? __builtin_amdgcn_exp2f(S[kt][j]) : 0.f; S[kt][j] = pv; ls += pv; }
;                             } else {
; #pragma unroll
;                                 for (int kt = 0; kt < 4; ++kt)
; #pragma unroll
;                                     for (int j = 0; j < 4; ++j) { const float pv = __builtin_amdgcn_exp2f(S[kt][j]); S[kt][j] = pv; ls += pv; }
;                             }
;                             lrun[qt] += ls;
.LBB0_247:
	v_and_b32_e32 v0, s16, v151
	v_cmp_ne_u32_e32 vcc, 0, v0
	s_cbranch_vccz .LBB0_254
	v_add_u32_e32 v0, s19, v97
	v_add_u32_e32 v0, 0xfffff830, v0
	v_cvt_f32_i32_e32 v0, v0
	v_add_u32_e32 v126, v139, v179
	ds_read_b128 v[162:165], v126
	ds_read_b128 v[166:169], v126 offset:64
	ds_read_b128 v[206:209], v126 offset:2304
	ds_read_b128 v[214:217], v126 offset:2368
	ds_read_b128 v[218:221], v126 offset:4608
	ds_read_b128 v[222:225], v126 offset:4672
	ds_read_b128 v[226:229], v126 offset:6912
	ds_read_b128 v[238:241], v126 offset:6976
	s_mov_b64 s[10:11], -1
	v_mul_f32_e32 v0, v186, v0
	v_cndmask_b32_e32 v122, v236, v0, vcc
	v_add_f32_e64 v6, v194, v122
	v_add_f32_e64 v7, v195, v122
	v_add_f32_e64 v4, v192, v122
	v_add_f32_e64 v5, v193, v122
	v_add_f32_e64 v10, v196, v122
	v_add_f32_e64 v11, v197, v122
	v_add_f32_e64 v8, v188, v122
	v_add_f32_e64 v9, v189, v122
	v_add_f32_e64 v14, v200, v122
	v_add_f32_e64 v15, v201, v122
	v_add_f32_e64 v12, v198, v122
	v_add_f32_e64 v13, v199, v122
	v_add_f32_e64 v124, v204, v122
	v_add_f32_e64 v125, v205, v122
	s_waitcnt lgkmcnt(7)
	v_mfma_f32_16x16x32_bf16 v[0:3], v[162:165], v[24:27], v[4:7]
	v_add_f32_e64 v123, v203, v122
	v_add_f32_e64 v122, v202, v122
	s_andn2_b64 vcc, exec, s[0:1]
	s_waitcnt lgkmcnt(6)
	v_mfma_f32_16x16x32_bf16 v[0:3], v[166:169], v[28:31], v[0:3]
	s_nop 7
	v_exp_f32_e32 v0, v0
	s_waitcnt lgkmcnt(5)
	v_mfma_f32_16x16x32_bf16 v[4:7], v[206:209], v[24:27], v[8:11]
	v_exp_f32_e32 v1, v1
	v_exp_f32_e32 v2, v2
	s_waitcnt lgkmcnt(4)
	v_mfma_f32_16x16x32_bf16 v[4:7], v[214:217], v[28:31], v[4:7]
	v_exp_f32_e32 v3, v3
	s_nop 6
	v_exp_f32_e32 v4, v4
	s_waitcnt lgkmcnt(3)
	v_mfma_f32_16x16x32_bf16 v[8:11], v[218:221], v[24:27], v[12:15]
	v_exp_f32_e32 v5, v5
	v_exp_f32_e32 v6, v6
	s_waitcnt lgkmcnt(2)
	v_mfma_f32_16x16x32_bf16 v[8:11], v[222:225], v[28:31], v[8:11]
	v_exp_f32_e32 v7, v7
	s_nop 6
	v_exp_f32_e32 v8, v8
	s_waitcnt lgkmcnt(1)
	v_mfma_f32_16x16x32_bf16 v[12:15], v[226:229], v[24:27], v[122:125]
	v_exp_f32_e32 v9, v9
	v_exp_f32_e32 v10, v10
	s_waitcnt lgkmcnt(0)
	v_mfma_f32_16x16x32_bf16 v[12:15], v[238:241], v[28:31], v[12:15]
	v_exp_f32_e32 v11, v11
	s_nop 6
	v_exp_f32_e32 v12, v12
	v_exp_f32_e32 v13, v13
	v_exp_f32_e32 v14, v14
	v_exp_f32_e32 v15, v15
	v_mov_b32_e32 v122, v238
	s_cbranch_vccnz .LBB0_250
	v_add_f32_e32 v122, 0, v0
	v_add_f32_e32 v122, v1, v122
	v_add_f32_e32 v122, v2, v122
	v_add_f32_e32 v122, v3, v122
	v_add_f32_e32 v122, v122, v4
	v_add_f32_e32 v122, v5, v122
	v_add_f32_e32 v122, v6, v122
	v_add_f32_e32 v122, v7, v122
	v_add_f32_e32 v122, v122, v8
	v_add_f32_e32 v122, v9, v122
	v_add_f32_e32 v122, v10, v122
	v_add_f32_e32 v122, v11, v122
	v_add_f32_e32 v122, v122, v12
	v_add_f32_e32 v122, v13, v122
	v_add_f32_e32 v122, v14, v122
	v_add_f32_e32 v122, v15, v122
	s_mov_b64 s[10:11], 0

; #define LAS __attribute__((address_space(3)))
; DI f32x4 mfma16(bf16x8 a, bf16x8 b, f32x4 c) { return __builtin_amdgcn_mfma_f32_16x16x32_bf16(a, b, c, 0, 0, 0); }
; DI void nsa_attn_phase(const int tid0, LAS unsigned char* lds, const P& p, int G, int c) {
;     ...
;                         const bool bsel = nvalid && ((br == 1) || ((sm[qt] >> n) & 1u));
;                         act[h][qt] = nvalid && ((br == 1) || (__ballot(bsel) != 0ull));
;                         pf[h][0][qt] = (bf16x8){0, 0, 0, 0, 0, 0, 0, 0}; pf[h][1][qt] = pf[h][0][qt];
;                         if (act[h][qt]) {
;                             const float sb = bsel ? slope2 * (float)(n * 64 + fq * 4 - tq[qt]) : -1e9f;
;                             f32x4 S[4];
; #pragma unroll
;                             for (int kt = 0; kt < 4; ++kt) { S[kt] = (f32x4){sb + sc16[kt * 4], sb + sc16[kt * 4 + 1], sb + sc16[kt * 4 + 2], sb + sc16[kt * 4 + 3]};
; #pragma unroll
;                                 for (int ks = 0; ks < 2; ++ks) { const bf16x8 kf = *(const LAS bf16x8*)(Kt + (kt * 16 + fr) * 72 + ks * 32 + fq * 8); S[kt] = mfma16(kf, Qf[qt][ks], S[kt]); } }
;                             float ls = 0.f;
;                             if (edge) {
; #pragma unroll
;                                 for (int kt = 0; kt < 4; ++kt)
; #pragma unroll
;                                     for (int j = 0; j < 4; ++j) { const int pos = n * 64 + kt * 16 + fq * 4 + j; const bool valid = (pos <= tq[qt]) && (br == 0 || pos > tq[qt] - 256);
;                                         const float pv = valid ? __builtin_amdgcn_exp2f(S[kt][j]) : 0.f; S[kt][j] = pv; ls += pv; }
;                             } else {
; #pragma unroll
;                                 for (int kt = 0; kt < 4; ++kt)
; #pragma unroll
;                                     for (int j = 0; j < 4; ++j) { const float pv = __builtin_amdgcn_exp2f(S[kt][j]); S[kt][j] = pv; ls += pv; }
;                             }
;                             lrun[qt] += ls;
.LBB0_255:
	s_cmp_lt_i32 s14, s44
	s_cselect_b64 s[16:17], -1, 0
	s_cmp_lg_u32 s15, 33
	s_cselect_b64 s[0:1], -1, 0
	s_lshl_b32 s60, 2, s14
	s_cmp_ge_i32 s14, s44
	v_add_u32_e32 v140, 64, v138
	s_mov_b64 s[12:13], 0
	s_cbranch_scc1 .LBB0_263
	v_and_b32_e32 v0, s60, v150
	v_cmp_ne_u32_e32 vcc, 0, v0
	s_cbranch_vccz .LBB0_270
	v_add_u32_e32 v0, s19, v97
	v_add_u32_e32 v0, 0xfffff880, v0
	v_cvt_f32_i32_e32 v0, v0
	v_add_u32_e32 v134, v139, v179
	ds_read_b128 v[162:165], v134 offset:18432
	ds_read_b128 v[166:169], v134 offset:18496
	ds_read_b128 v[206:209], v134 offset:20736
	ds_read_b128 v[214:217], v134 offset:20800
	ds_read_b128 v[218:221], v134 offset:23040
	ds_read_b128 v[222:225], v134 offset:23104
	ds_read_b128 v[226:229], v134 offset:25344
	ds_read_b128 v[238:241], v134 offset:25408
	s_mov_b64 s[14:15], -1
	v_mul_f32_e32 v0, v186, v0
	v_cndmask_b32_e32 v130, v236, v0, vcc
	v_add_f32_e64 v6, v194, v130
	v_add_f32_e64 v7, v195, v130
	v_add_f32_e64 v4, v192, v130
	v_add_f32_e64 v5, v193, v130
	v_add_f32_e64 v10, v196, v130
	v_add_f32_e64 v11, v197, v130
	v_add_f32_e64 v8, v188, v130
	v_add_f32_e64 v9, v189, v130
	v_add_f32_e64 v14, v200, v130
	v_add_f32_e64 v15, v201, v130
	v_add_f32_e64 v12, v198, v130
	v_add_f32_e64 v13, v199, v130
	v_add_f32_e64 v132, v204, v130
	v_add_f32_e64 v133, v205, v130
	s_waitcnt lgkmcnt(7)
	v_mfma_f32_16x16x32_bf16 v[0:3], v[162:165], v[16:19], v[4:7]
	v_add_f32_e64 v131, v203, v130
	v_add_f32_e64 v130, v202, v130
	s_andn2_b64 vcc, exec, s[0:1]
	s_waitcnt lgkmcnt(6)
	v_mfma_f32_16x16x32_bf16 v[0:3], v[166:169], v[20:23], v[0:3]
	s_nop 7
	v_exp_f32_e32 v0, v0
	s_waitcnt lgkmcnt(5)
	v_mfma_f32_16x16x32_bf16 v[4:7], v[206:209], v[16:19], v[8:11]
	v_exp_f32_e32 v1, v1
	v_exp_f32_e32 v2, v2
	s_waitcnt lgkmcnt(4)
	v_mfma_f32_16x16x32_bf16 v[4:7], v[214:217], v[20:23], v[4:7]
	v_exp_f32_e32 v3, v3
	s_nop 6
	v_exp_f32_e32 v4, v4
	s_waitcnt lgkmcnt(3)
	v_mfma_f32_16x16x32_bf16 v[8:11], v[218:221], v[16:19], v[12:15]
	v_exp_f32_e32 v5, v5
	v_exp_f32_e32 v6, v6
	s_waitcnt lgkmcnt(2)
	v_mfma_f32_16x16x32_bf16 v[8:11], v[222:225], v[20:23], v[8:11]
	v_exp_f32_e32 v7, v7
	s_nop 6
	v_exp_f32_e32 v8, v8
	s_waitcnt lgkmcnt(1)
	v_mfma_f32_16x16x32_bf16 v[12:15], v[226:229], v[16:19], v[130:133]
	v_exp_f32_e32 v9, v9
	v_exp_f32_e32 v10, v10
	s_waitcnt lgkmcnt(0)
	v_mfma_f32_16x16x32_bf16 v[12:15], v[238:241], v[20:23], v[12:15]
	v_exp_f32_e32 v11, v11
	s_nop 6
	v_exp_f32_e32 v12, v12
	v_exp_f32_e32 v13, v13
	v_exp_f32_e32 v14, v14
	v_exp_f32_e32 v15, v15
	v_mov_b32_e32 v130, v238
	s_cbranch_vccnz .LBB0_259
	v_add_f32_e32 v130, 0, v0
	v_add_f32_e32 v130, v1, v130
	v_add_f32_e32 v130, v2, v130
	v_add_f32_e32 v130, v3, v130
	v_add_f32_e32 v130, v130, v4
	v_add_f32_e32 v130, v5, v130
	v_add_f32_e32 v130, v6, v130
	v_add_f32_e32 v130, v7, v130
	v_add_f32_e32 v130, v130, v8
	v_add_f32_e32 v130, v9, v130
	v_add_f32_e32 v130, v10, v130
	v_add_f32_e32 v130, v11, v130
	v_add_f32_e32 v130, v130, v12
	v_add_f32_e32 v130, v13, v130
	v_add_f32_e32 v130, v14, v130
	v_add_f32_e32 v130, v15, v130
	s_mov_b64 s[14:15], 0

; #define LAS __attribute__((address_space(3)))
; DI f32x4 mfma16(bf16x8 a, bf16x8 b, f32x4 c) { return __builtin_amdgcn_mfma_f32_16x16x32_bf16(a, b, c, 0, 0, 0); }
; DI void nsa_attn_phase(const int tid0, LAS unsigned char* lds, const P& p, int G, int c) {
;     ...
;                         const bool bsel = nvalid && ((br == 1) || ((sm[qt] >> n) & 1u));
;                         act[h][qt] = nvalid && ((br == 1) || (__ballot(bsel) != 0ull));
;                         pf[h][0][qt] = (bf16x8){0, 0, 0, 0, 0, 0, 0, 0}; pf[h][1][qt] = pf[h][0][qt];
;                         if (act[h][qt]) {
;                             const float sb = bsel ? slope2 * (float)(n * 64 + fq * 4 - tq[qt]) : -1e9f;
;                             f32x4 S[4];
; #pragma unroll
;                             for (int kt = 0; kt < 4; ++kt) { S[kt] = (f32x4){sb + sc16[kt * 4], sb + sc16[kt * 4 + 1], sb + sc16[kt * 4 + 2], sb + sc16[kt * 4 + 3]};
; #pragma unroll
;                                 for (int ks = 0; ks < 2; ++ks) { const bf16x8 kf = *(const LAS bf16x8*)(Kt + (kt * 16 + fr) * 72 + ks * 32 + fq * 8); S[kt] = mfma16(kf, Qf[qt][ks], S[kt]); } }
;                             float ls = 0.f;
;                             if (edge) {
; #pragma unroll
;                                 for (int kt = 0; kt < 4; ++kt)
; #pragma unroll
;                                     for (int j = 0; j < 4; ++j) { const int pos = n * 64 + kt * 16 + fq * 4 + j; const bool valid = (pos <= tq[qt]) && (br == 0 || pos > tq[qt] - 256);
;                                         const float pv = valid ? __builtin_amdgcn_exp2f(S[kt][j]) : 0.f; S[kt][j] = pv; ls += pv; }
;                             } else {
; #pragma unroll
;                                 for (int kt = 0; kt < 4; ++kt)
; #pragma unroll
;                                     for (int j = 0; j < 4; ++j) { const float pv = __builtin_amdgcn_exp2f(S[kt][j]); S[kt][j] = pv; ls += pv; }
;                             }
;                             lrun[qt] += ls;
.LBB0_264:
	v_and_b32_e32 v0, s60, v151
	v_cmp_ne_u32_e32 vcc, 0, v0
	s_cbranch_vccz .LBB0_271
	v_add_u32_e32 v0, s19, v97
	v_add_u32_e32 v0, 0xfffff870, v0
	v_cvt_f32_i32_e32 v0, v0
	v_add_u32_e32 v139, v139, v179
	ds_read_b128 v[162:165], v139 offset:18432
	ds_read_b128 v[166:169], v139 offset:18496
	ds_read_b128 v[206:209], v139 offset:20736
	ds_read_b128 v[214:217], v139 offset:20800
	ds_read_b128 v[218:221], v139 offset:23040
	ds_read_b128 v[222:225], v139 offset:23104
	ds_read_b128 v[226:229], v139 offset:25344
	ds_read_b128 v[238:241], v139 offset:25408
	s_mov_b64 s[12:13], -1
	v_mul_f32_e32 v0, v186, v0
	v_cndmask_b32_e32 v158, v236, v0, vcc
	v_add_f32_e64 v6, v194, v158
	v_add_f32_e64 v7, v195, v158
	v_add_f32_e64 v4, v192, v158
	v_add_f32_e64 v5, v193, v158
	v_add_f32_e64 v10, v196, v158
	v_add_f32_e64 v11, v197, v158
	v_add_f32_e64 v8, v188, v158
	v_add_f32_e64 v9, v189, v158
	v_add_f32_e64 v14, v200, v158
	v_add_f32_e64 v15, v201, v158
	v_add_f32_e64 v12, v198, v158
	v_add_f32_e64 v13, v199, v158
	v_add_f32_e64 v160, v204, v158
	v_add_f32_e64 v161, v205, v158
	s_waitcnt lgkmcnt(7)
	v_mfma_f32_16x16x32_bf16 v[0:3], v[162:165], v[24:27], v[4:7]
	v_add_f32_e64 v159, v203, v158
	v_add_f32_e64 v158, v202, v158
	s_andn2_b64 vcc, exec, s[0:1]
	s_waitcnt lgkmcnt(6)
	v_mfma_f32_16x16x32_bf16 v[0:3], v[166:169], v[28:31], v[0:3]
	s_nop 7
	v_exp_f32_e32 v0, v0
	s_waitcnt lgkmcnt(5)
	v_mfma_f32_16x16x32_bf16 v[4:7], v[206:209], v[24:27], v[8:11]
	v_exp_f32_e32 v1, v1
	v_exp_f32_e32 v2, v2
	s_waitcnt lgkmcnt(4)
	v_mfma_f32_16x16x32_bf16 v[4:7], v[214:217], v[28:31], v[4:7]
	v_exp_f32_e32 v3, v3
	s_nop 6
	v_exp_f32_e32 v4, v4
	s_waitcnt lgkmcnt(3)
	v_mfma_f32_16x16x32_bf16 v[8:11], v[218:221], v[24:27], v[12:15]
	v_exp_f32_e32 v5, v5
	v_exp_f32_e32 v6, v6
	s_waitcnt lgkmcnt(2)
	v_mfma_f32_16x16x32_bf16 v[8:11], v[222:225], v[28:31], v[8:11]
	v_exp_f32_e32 v7, v7
	s_nop 6
	v_exp_f32_e32 v8, v8
	s_waitcnt lgkmcnt(1)
	v_mfma_f32_16x16x32_bf16 v[12:15], v[226:229], v[24:27], v[158:161]
	v_exp_f32_e32 v9, v9
	v_exp_f32_e32 v10, v10
	s_waitcnt lgkmcnt(0)
	v_mfma_f32_16x16x32_bf16 v[12:15], v[238:241], v[28:31], v[12:15]
	v_exp_f32_e32 v11, v11
	s_nop 6
	v_exp_f32_e32 v12, v12
	v_exp_f32_e32 v13, v13
	v_exp_f32_e32 v14, v14
	v_exp_f32_e32 v15, v15
	s_cbranch_vccnz .LBB0_267
	v_add_f32_e32 v139, 0, v0
	v_add_f32_e32 v139, v1, v139
	v_add_f32_e32 v139, v2, v139
	v_add_f32_e32 v139, v3, v139
	v_add_f32_e32 v139, v139, v4
	v_add_f32_e32 v139, v5, v139
	v_add_f32_e32 v139, v6, v139
	v_add_f32_e32 v139, v7, v139
	v_add_f32_e32 v139, v139, v8
	v_add_f32_e32 v139, v9, v139
	v_add_f32_e32 v139, v10, v139
	v_add_f32_e32 v139, v11, v139
	v_add_f32_e32 v139, v139, v12
	v_add_f32_e32 v139, v13, v139
	v_add_f32_e32 v139, v14, v139
	v_add_f32_e32 v139, v15, v139
	s_mov_b64 s[12:13], 0

; #define LAS __attribute__((address_space(3)))
; DI f32x4 mfma16(bf16x8 a, bf16x8 b, f32x4 c) { return __builtin_amdgcn_mfma_f32_16x16x32_bf16(a, b, c, 0, 0, 0); }
; DI void nsa_attn_phase(const int tid0, LAS unsigned char* lds, const P& p, int G, int c) {
;     ...
;                         const bool bsel = nvalid && ((br == 1) || ((sm[qt] >> n) & 1u));
;                         act[h][qt] = nvalid && ((br == 1) || (__ballot(bsel) != 0ull));
;                         pf[h][0][qt] = (bf16x8){0, 0, 0, 0, 0, 0, 0, 0}; pf[h][1][qt] = pf[h][0][qt];
;                         if (act[h][qt]) {
;                             const float sb = bsel ? slope2 * (float)(n * 64 + fq * 4 - tq[qt]) : -1e9f;
;                             f32x4 S[4];
; #pragma unroll
;                             for (int kt = 0; kt < 4; ++kt) { S[kt] = (f32x4){sb + sc16[kt * 4], sb + sc16[kt * 4 + 1], sb + sc16[kt * 4 + 2], sb + sc16[kt * 4 + 3]};
; #pragma unroll
;                                 for (int ks = 0; ks < 2; ++ks) { const bf16x8 kf = *(const LAS bf16x8*)(Kt + (kt * 16 + fr) * 72 + ks * 32 + fq * 8); S[kt] = mfma16(kf, Qf[qt][ks], S[kt]); } }
;                             float ls = 0.f;
;                             if (edge) {
; #pragma unroll
;                                 for (int kt = 0; kt < 4; ++kt)
; #pragma unroll
;                                     for (int j = 0; j < 4; ++j) { const int pos = n * 64 + kt * 16 + fq * 4 + j; const bool valid = (pos <= tq[qt]) && (br == 0 || pos > tq[qt] - 256);
;                                         const float pv = valid ? __builtin_amdgcn_exp2f(S[kt][j]) : 0.f; S[kt][j] = pv; ls += pv; }
;                             } else {
; #pragma unroll
;                                 for (int kt = 0; kt < 4; ++kt)
; #pragma unroll
;                                     for (int j = 0; j < 4; ++j) { const float pv = __builtin_amdgcn_exp2f(S[kt][j]); S[kt][j] = pv; ls += pv; }
;                             }
;                             lrun[qt] += ls;
.LBB0_346:
	s_bitcmp0_b32 s0, 0
	s_cselect_b64 s[10:11], -1, 0
	s_and_b64 s[0:1], s[10:11], exec
	s_cselect_b32 s0, s94, 0
	s_add_i32 s18, s15, -3
	s_add_i32 s19, s41, s15
	s_cmp_le_i32 s18, s44
	s_cselect_b64 s[6:7], -1, 0
	s_cmp_lg_u32 s19, 34
	v_add_u32_e32 v0, s0, v187
	s_cselect_b64 s[0:1], -1, 0
	s_cmp_lg_u32 s19, 30
	s_cselect_b64 s[4:5], -1, 0
	s_and_b64 s[0:1], s[0:1], s[4:5]
	v_add_u32_e32 v169, v0, v179
	v_cndmask_b32_e64 v0, 0, 1, s[0:1]
	s_cmp_gt_i32 s18, s44
	v_add_u32_e32 v168, s16, v190
	v_cmp_ne_u32_e64 s[0:1], 1, v0
	s_cbranch_scc1 .LBB0_353
	ds_read_b128 v[226:229], v169
	ds_read_b128 v[238:241], v169 offset:64
	ds_read_b128 v[242:245], v169 offset:2304
	ds_read_b128 v[246:249], v169 offset:2368
	s_movk_i32 s4, 0xf840
	v_add3_u32 v0, v190, v220, s4
	v_cvt_f32_i32_e32 v0, v0
	s_mov_b64 s[4:5], -1
	s_and_b64 vcc, exec, s[0:1]
	v_mul_f32_e32 v144, v186, v0
	v_add_f32_e64 v6, v194, v144
	v_add_f32_e64 v7, v195, v144
	v_add_f32_e64 v4, v192, v144
	v_add_f32_e64 v5, v193, v144
	v_add_f32_e64 v10, v196, v144
	v_add_f32_e64 v11, v197, v144
	v_add_f32_e64 v8, v188, v144
	v_add_f32_e64 v9, v189, v144
	v_add_f32_e64 v14, v200, v144
	v_add_f32_e64 v15, v201, v144
	v_add_f32_e64 v12, v198, v144
	v_add_f32_e64 v13, v199, v144
	v_add_f32_e64 v146, v204, v144
	v_add_f32_e64 v147, v205, v144
	s_waitcnt lgkmcnt(3)
	v_mfma_f32_16x16x32_bf16 v[0:3], v[226:229], v[16:19], v[4:7]
	ds_read_b128 v[226:229], v169 offset:4608
	v_add_f32_e64 v145, v203, v144
	v_add_f32_e64 v144, v202, v144
	s_waitcnt lgkmcnt(3)
	v_mfma_f32_16x16x32_bf16 v[0:3], v[238:241], v[20:23], v[0:3]
	ds_read_b128 v[238:241], v169 offset:4672
	s_nop 6
	v_exp_f32_e32 v0, v0
	s_waitcnt lgkmcnt(3)
	v_mfma_f32_16x16x32_bf16 v[4:7], v[242:245], v[16:19], v[8:11]
	ds_read_b128 v[242:245], v169 offset:6912
	v_exp_f32_e32 v1, v1
	v_exp_f32_e32 v2, v2
	s_waitcnt lgkmcnt(3)
	v_mfma_f32_16x16x32_bf16 v[4:7], v[246:249], v[20:23], v[4:7]
	ds_read_b128 v[246:249], v169 offset:6976
	v_exp_f32_e32 v3, v3
	s_nop 5
	v_exp_f32_e32 v4, v4
	s_waitcnt lgkmcnt(3)
	v_mfma_f32_16x16x32_bf16 v[8:11], v[226:229], v[16:19], v[12:15]
	v_exp_f32_e32 v5, v5
	v_exp_f32_e32 v6, v6
	s_waitcnt lgkmcnt(2)
	v_mfma_f32_16x16x32_bf16 v[8:11], v[238:241], v[20:23], v[8:11]
	v_exp_f32_e32 v7, v7
	s_nop 6
	v_exp_f32_e32 v8, v8
	s_waitcnt lgkmcnt(1)
	v_mfma_f32_16x16x32_bf16 v[12:15], v[242:245], v[16:19], v[144:147]
	v_exp_f32_e32 v9, v9
	v_exp_f32_e32 v10, v10
	s_waitcnt lgkmcnt(0)
	v_mfma_f32_16x16x32_bf16 v[12:15], v[246:249], v[20:23], v[12:15]
	v_exp_f32_e32 v11, v11
	s_nop 6
	v_exp_f32_e32 v12, v12
	v_exp_f32_e32 v13, v13
	v_exp_f32_e32 v14, v14
	v_exp_f32_e32 v15, v15
	v_mov_b32_e32 v144, v246
	s_cbranch_vccnz .LBB0_349
	v_add_f32_e32 v144, 0, v0
	v_add_f32_e32 v144, v1, v144
	v_add_f32_e32 v144, v2, v144
	v_add_f32_e32 v144, v3, v144
	v_add_f32_e32 v144, v144, v4
	v_add_f32_e32 v144, v5, v144
	v_add_f32_e32 v144, v6, v144
	v_add_f32_e32 v144, v7, v144
	v_add_f32_e32 v144, v144, v8
	v_add_f32_e32 v144, v9, v144
	v_add_f32_e32 v144, v10, v144
	v_add_f32_e32 v144, v11, v144
	v_add_f32_e32 v144, v144, v12
	v_add_f32_e32 v144, v13, v144
	v_add_f32_e32 v144, v14, v144
	v_add_f32_e32 v144, v15, v144
	s_mov_b64 s[4:5], 0

; #define LAS __attribute__((address_space(3)))
; DI f32x4 mfma16(bf16x8 a, bf16x8 b, f32x4 c) { return __builtin_amdgcn_mfma_f32_16x16x32_bf16(a, b, c, 0, 0, 0); }
; DI void nsa_attn_phase(const int tid0, LAS unsigned char* lds, const P& p, int G, int c) {
;     ...
;                         const bool bsel = nvalid && ((br == 1) || ((sm[qt] >> n) & 1u));
;                         act[h][qt] = nvalid && ((br == 1) || (__ballot(bsel) != 0ull));
;                         pf[h][0][qt] = (bf16x8){0, 0, 0, 0, 0, 0, 0, 0}; pf[h][1][qt] = pf[h][0][qt];
;                         if (act[h][qt]) {
;                             const float sb = bsel ? slope2 * (float)(n * 64 + fq * 4 - tq[qt]) : -1e9f;
;                             f32x4 S[4];
; #pragma unroll
;                             for (int kt = 0; kt < 4; ++kt) { S[kt] = (f32x4){sb + sc16[kt * 4], sb + sc16[kt * 4 + 1], sb + sc16[kt * 4 + 2], sb + sc16[kt * 4 + 3]};
; #pragma unroll
;                                 for (int ks = 0; ks < 2; ++ks) { const bf16x8 kf = *(const LAS bf16x8*)(Kt + (kt * 16 + fr) * 72 + ks * 32 + fq * 8); S[kt] = mfma16(kf, Qf[qt][ks], S[kt]); } }
;                             float ls = 0.f;
;                             if (edge) {
; #pragma unroll
;                                 for (int kt = 0; kt < 4; ++kt)
; #pragma unroll
;                                     for (int j = 0; j < 4; ++j) { const int pos = n * 64 + kt * 16 + fq * 4 + j; const bool valid = (pos <= tq[qt]) && (br == 0 || pos > tq[qt] - 256);
;                                         const float pv = valid ? __builtin_amdgcn_exp2f(S[kt][j]) : 0.f; S[kt][j] = pv; ls += pv; }
;                             } else {
; #pragma unroll
;                                 for (int kt = 0; kt < 4; ++kt)
; #pragma unroll
;                                     for (int j = 0; j < 4; ++j) { const float pv = __builtin_amdgcn_exp2f(S[kt][j]); S[kt][j] = pv; ls += pv; }
;                             }
;                             lrun[qt] += ls;
.LBB0_354:
	ds_read_b128 v[226:229], v169
	ds_read_b128 v[238:241], v169 offset:64
	ds_read_b128 v[242:245], v169 offset:2304
	ds_read_b128 v[246:249], v169 offset:2368
	s_movk_i32 s6, 0xf830
	v_add3_u32 v0, v190, v220, s6
	v_cvt_f32_i32_e32 v0, v0
	s_mov_b64 s[6:7], -1
	s_and_b64 vcc, exec, s[0:1]
	v_mul_f32_e32 v152, v186, v0
	v_add_f32_e64 v6, v194, v152
	v_add_f32_e64 v7, v195, v152
	v_add_f32_e64 v4, v192, v152
	v_add_f32_e64 v5, v193, v152
	v_add_f32_e64 v10, v196, v152
	v_add_f32_e64 v11, v197, v152
	v_add_f32_e64 v8, v188, v152
	v_add_f32_e64 v9, v189, v152
	v_add_f32_e64 v14, v200, v152
	v_add_f32_e64 v15, v201, v152
	v_add_f32_e64 v12, v198, v152
	v_add_f32_e64 v13, v199, v152
	v_add_f32_e64 v154, v204, v152
	v_add_f32_e64 v155, v205, v152
	s_waitcnt lgkmcnt(3)
	v_mfma_f32_16x16x32_bf16 v[0:3], v[226:229], v[24:27], v[4:7]
	ds_read_b128 v[226:229], v169 offset:4608
	v_add_f32_e64 v153, v203, v152
	v_add_f32_e64 v152, v202, v152
	s_waitcnt lgkmcnt(3)
	v_mfma_f32_16x16x32_bf16 v[0:3], v[238:241], v[28:31], v[0:3]
	ds_read_b128 v[238:241], v169 offset:4672
	s_nop 6
	v_exp_f32_e32 v0, v0
	s_waitcnt lgkmcnt(3)
	v_mfma_f32_16x16x32_bf16 v[4:7], v[242:245], v[24:27], v[8:11]
	ds_read_b128 v[242:245], v169 offset:6912
	v_exp_f32_e32 v1, v1
	v_exp_f32_e32 v2, v2
	s_waitcnt lgkmcnt(3)
	v_mfma_f32_16x16x32_bf16 v[4:7], v[246:249], v[28:31], v[4:7]
	ds_read_b128 v[246:249], v169 offset:6976
	v_exp_f32_e32 v3, v3
	s_nop 5
	v_exp_f32_e32 v4, v4
	s_waitcnt lgkmcnt(3)
	v_mfma_f32_16x16x32_bf16 v[8:11], v[226:229], v[24:27], v[12:15]
	v_exp_f32_e32 v5, v5
	v_exp_f32_e32 v6, v6
	s_waitcnt lgkmcnt(2)
	v_mfma_f32_16x16x32_bf16 v[8:11], v[238:241], v[28:31], v[8:11]
	v_exp_f32_e32 v7, v7
	s_nop 6
	v_exp_f32_e32 v8, v8
	s_waitcnt lgkmcnt(1)
	v_mfma_f32_16x16x32_bf16 v[12:15], v[242:245], v[24:27], v[152:155]
	v_exp_f32_e32 v9, v9
	v_exp_f32_e32 v10, v10
	s_waitcnt lgkmcnt(0)
	v_mfma_f32_16x16x32_bf16 v[12:15], v[246:249], v[28:31], v[12:15]
	v_exp_f32_e32 v11, v11
	s_nop 6
	v_exp_f32_e32 v12, v12
	v_exp_f32_e32 v13, v13
	v_exp_f32_e32 v14, v14
	v_exp_f32_e32 v15, v15
	v_mov_b32_e32 v152, v246
	s_cbranch_vccnz .LBB0_356
	v_add_f32_e32 v152, 0, v0
	v_add_f32_e32 v152, v1, v152
	v_add_f32_e32 v152, v2, v152
	v_add_f32_e32 v152, v3, v152
	v_add_f32_e32 v152, v152, v4
	v_add_f32_e32 v152, v5, v152
	v_add_f32_e32 v152, v6, v152
	v_add_f32_e32 v152, v7, v152
	v_add_f32_e32 v152, v152, v8
	v_add_f32_e32 v152, v9, v152
	v_add_f32_e32 v152, v10, v152
	v_add_f32_e32 v152, v11, v152
	v_add_f32_e32 v152, v152, v12
	v_add_f32_e32 v152, v13, v152
	v_add_f32_e32 v152, v14, v152
	v_add_f32_e32 v152, v15, v152
	s_mov_b64 s[6:7], 0

; #define LAS __attribute__((address_space(3)))
; DI f32x4 mfma16(bf16x8 a, bf16x8 b, f32x4 c) { return __builtin_amdgcn_mfma_f32_16x16x32_bf16(a, b, c, 0, 0, 0); }
; DI void nsa_attn_phase(const int tid0, LAS unsigned char* lds, const P& p, int G, int c) {
;     ...
;                         const bool bsel = nvalid && ((br == 1) || ((sm[qt] >> n) & 1u));
;                         act[h][qt] = nvalid && ((br == 1) || (__ballot(bsel) != 0ull));
;                         pf[h][0][qt] = (bf16x8){0, 0, 0, 0, 0, 0, 0, 0}; pf[h][1][qt] = pf[h][0][qt];
;                         if (act[h][qt]) {
;                             const float sb = bsel ? slope2 * (float)(n * 64 + fq * 4 - tq[qt]) : -1e9f;
;                             f32x4 S[4];
; #pragma unroll
;                             for (int kt = 0; kt < 4; ++kt) { S[kt] = (f32x4){sb + sc16[kt * 4], sb + sc16[kt * 4 + 1], sb + sc16[kt * 4 + 2], sb + sc16[kt * 4 + 3]};
; #pragma unroll
;                                 for (int ks = 0; ks < 2; ++ks) { const bf16x8 kf = *(const LAS bf16x8*)(Kt + (kt * 16 + fr) * 72 + ks * 32 + fq * 8); S[kt] = mfma16(kf, Qf[qt][ks], S[kt]); } }
;                             float ls = 0.f;
;                             if (edge) {
; #pragma unroll
;                                 for (int kt = 0; kt < 4; ++kt)
; #pragma unroll
;                                     for (int j = 0; j < 4; ++j) { const int pos = n * 64 + kt * 16 + fq * 4 + j; const bool valid = (pos <= tq[qt]) && (br == 0 || pos > tq[qt] - 256);
;                                         const float pv = valid ? __builtin_amdgcn_exp2f(S[kt][j]) : 0.f; S[kt][j] = pv; ls += pv; }
;                             } else {
; #pragma unroll
;                                 for (int kt = 0; kt < 4; ++kt)
; #pragma unroll
;                                     for (int j = 0; j < 4; ++j) { const float pv = __builtin_amdgcn_exp2f(S[kt][j]); S[kt][j] = pv; ls += pv; }
;                             }
;                             lrun[qt] += ls;
.LBB0_359:
	s_cmp_lt_i32 s18, s44
	s_cselect_b64 s[12:13], -1, 0
	s_cmp_lg_u32 s19, 33
	s_cselect_b64 s[0:1], -1, 0
	s_cmp_lg_u32 s19, 29
	s_cselect_b64 s[6:7], -1, 0
	s_and_b64 s[0:1], s[0:1], s[6:7]
	v_cndmask_b32_e64 v0, 0, 1, s[0:1]
	s_cmp_ge_i32 s18, s44
	v_add_u32_e32 v170, 64, v168
	v_cmp_ne_u32_e64 s[0:1], 1, v0
	s_cbranch_scc1 .LBB0_366
	ds_read_b128 v[226:229], v169 offset:18432
	ds_read_b128 v[238:241], v169 offset:18496
	ds_read_b128 v[242:245], v169 offset:20736
	ds_read_b128 v[246:249], v169 offset:20800
	s_movk_i32 s6, 0xf880
	v_add3_u32 v0, v190, v220, s6
	v_cvt_f32_i32_e32 v0, v0
	s_mov_b64 s[6:7], -1
	s_and_b64 vcc, exec, s[0:1]
	v_mul_f32_e32 v160, v186, v0
	v_add_f32_e64 v6, v194, v160
	v_add_f32_e64 v7, v195, v160
	v_add_f32_e64 v4, v192, v160
	v_add_f32_e64 v5, v193, v160
	v_add_f32_e64 v10, v196, v160
	v_add_f32_e64 v11, v197, v160
	v_add_f32_e64 v8, v188, v160
	v_add_f32_e64 v9, v189, v160
	v_add_f32_e64 v14, v200, v160
	v_add_f32_e64 v15, v201, v160
	v_add_f32_e64 v12, v198, v160
	v_add_f32_e64 v13, v199, v160
	v_add_f32_e64 v162, v204, v160
	v_add_f32_e64 v163, v205, v160
	s_waitcnt lgkmcnt(3)
	v_mfma_f32_16x16x32_bf16 v[0:3], v[226:229], v[16:19], v[4:7]
	ds_read_b128 v[226:229], v169 offset:23040
	v_add_f32_e64 v161, v203, v160
	v_add_f32_e64 v160, v202, v160
	s_waitcnt lgkmcnt(3)
	v_mfma_f32_16x16x32_bf16 v[0:3], v[238:241], v[20:23], v[0:3]
	ds_read_b128 v[238:241], v169 offset:23104
	s_nop 6
	v_exp_f32_e32 v0, v0
	s_waitcnt lgkmcnt(3)
	v_mfma_f32_16x16x32_bf16 v[4:7], v[242:245], v[16:19], v[8:11]
	ds_read_b128 v[242:245], v169 offset:25344
	v_exp_f32_e32 v1, v1
	v_exp_f32_e32 v2, v2
	s_waitcnt lgkmcnt(3)
	v_mfma_f32_16x16x32_bf16 v[4:7], v[246:249], v[20:23], v[4:7]
	ds_read_b128 v[246:249], v169 offset:25408
	v_exp_f32_e32 v3, v3
	s_nop 5
	v_exp_f32_e32 v4, v4
	s_waitcnt lgkmcnt(3)
	v_mfma_f32_16x16x32_bf16 v[8:11], v[226:229], v[16:19], v[12:15]
	v_exp_f32_e32 v5, v5
	v_exp_f32_e32 v6, v6
	s_waitcnt lgkmcnt(2)
	v_mfma_f32_16x16x32_bf16 v[8:11], v[238:241], v[20:23], v[8:11]
	v_exp_f32_e32 v7, v7
	s_nop 6
	v_exp_f32_e32 v8, v8
	s_waitcnt lgkmcnt(1)
	v_mfma_f32_16x16x32_bf16 v[12:15], v[242:245], v[16:19], v[160:163]
	v_exp_f32_e32 v9, v9
	v_exp_f32_e32 v10, v10
	s_waitcnt lgkmcnt(0)
	v_mfma_f32_16x16x32_bf16 v[12:15], v[246:249], v[20:23], v[12:15]
	v_exp_f32_e32 v11, v11
	s_nop 6
	v_exp_f32_e32 v12, v12
	v_exp_f32_e32 v13, v13
	v_exp_f32_e32 v14, v14
	v_exp_f32_e32 v15, v15
	v_mov_b32_e32 v160, v246
	s_cbranch_vccnz .LBB0_362
	v_add_f32_e32 v160, 0, v0
	v_add_f32_e32 v160, v1, v160
	v_add_f32_e32 v160, v2, v160
	v_add_f32_e32 v160, v3, v160
	v_add_f32_e32 v160, v160, v4
	v_add_f32_e32 v160, v5, v160
	v_add_f32_e32 v160, v6, v160
	v_add_f32_e32 v160, v7, v160
	v_add_f32_e32 v160, v160, v8
	v_add_f32_e32 v160, v9, v160
	v_add_f32_e32 v160, v10, v160
	v_add_f32_e32 v160, v11, v160
	v_add_f32_e32 v160, v160, v12
	v_add_f32_e32 v160, v13, v160
	v_add_f32_e32 v160, v14, v160
	v_add_f32_e32 v160, v15, v160
	s_mov_b64 s[6:7], 0

; #define LAS __attribute__((address_space(3)))
; DI f32x4 mfma16(bf16x8 a, bf16x8 b, f32x4 c) { return __builtin_amdgcn_mfma_f32_16x16x32_bf16(a, b, c, 0, 0, 0); }
; DI void nsa_attn_phase(const int tid0, LAS unsigned char* lds, const P& p, int G, int c) {
;     ...
;                         const bool bsel = nvalid && ((br == 1) || ((sm[qt] >> n) & 1u));
;                         act[h][qt] = nvalid && ((br == 1) || (__ballot(bsel) != 0ull));
;                         pf[h][0][qt] = (bf16x8){0, 0, 0, 0, 0, 0, 0, 0}; pf[h][1][qt] = pf[h][0][qt];
;                         if (act[h][qt]) {
;                             const float sb = bsel ? slope2 * (float)(n * 64 + fq * 4 - tq[qt]) : -1e9f;
;                             f32x4 S[4];
; #pragma unroll
;                             for (int kt = 0; kt < 4; ++kt) { S[kt] = (f32x4){sb + sc16[kt * 4], sb + sc16[kt * 4 + 1], sb + sc16[kt * 4 + 2], sb + sc16[kt * 4 + 3]};
; #pragma unroll
;                                 for (int ks = 0; ks < 2; ++ks) { const bf16x8 kf = *(const LAS bf16x8*)(Kt + (kt * 16 + fr) * 72 + ks * 32 + fq * 8); S[kt] = mfma16(kf, Qf[qt][ks], S[kt]); } }
;                             float ls = 0.f;
;                             if (edge) {
; #pragma unroll
;                                 for (int kt = 0; kt < 4; ++kt)
; #pragma unroll
;                                     for (int j = 0; j < 4; ++j) { const int pos = n * 64 + kt * 16 + fq * 4 + j; const bool valid = (pos <= tq[qt]) && (br == 0 || pos > tq[qt] - 256);
;                                         const float pv = valid ? __builtin_amdgcn_exp2f(S[kt][j]) : 0.f; S[kt][j] = pv; ls += pv; }
;                             } else {
; #pragma unroll
;                                 for (int kt = 0; kt < 4; ++kt)
; #pragma unroll
;                                     for (int j = 0; j < 4; ++j) { const float pv = __builtin_amdgcn_exp2f(S[kt][j]); S[kt][j] = pv; ls += pv; }
;                             }
;                             lrun[qt] += ls;
.LBB0_367:
	ds_read_b128 v[226:229], v169 offset:18432
	ds_read_b128 v[238:241], v169 offset:18496
	ds_read_b128 v[242:245], v169 offset:20736
	ds_read_b128 v[246:249], v169 offset:20800
	s_movk_i32 s12, 0xf870
	v_add3_u32 v0, v190, v220, s12
	v_cvt_f32_i32_e32 v0, v0
	s_mov_b64 s[12:13], -1
	s_and_b64 vcc, exec, s[0:1]
	v_mul_f32_e32 v222, v186, v0
	v_add_f32_e64 v6, v194, v222
	v_add_f32_e64 v7, v195, v222
	v_add_f32_e64 v4, v192, v222
	v_add_f32_e64 v5, v193, v222
	v_add_f32_e64 v10, v196, v222
	v_add_f32_e64 v11, v197, v222
	v_add_f32_e64 v8, v188, v222
	v_add_f32_e64 v9, v189, v222
	v_add_f32_e64 v14, v200, v222
	v_add_f32_e64 v15, v201, v222
	v_add_f32_e64 v12, v198, v222
	v_add_f32_e64 v13, v199, v222
	v_add_f32_e64 v224, v204, v222
	v_add_f32_e64 v225, v205, v222
	s_waitcnt lgkmcnt(3)
	v_mfma_f32_16x16x32_bf16 v[0:3], v[226:229], v[24:27], v[4:7]
	ds_read_b128 v[226:229], v169 offset:23040
	v_add_f32_e64 v223, v203, v222
	v_add_f32_e64 v222, v202, v222
	s_waitcnt lgkmcnt(3)
	v_mfma_f32_16x16x32_bf16 v[0:3], v[238:241], v[28:31], v[0:3]
	ds_read_b128 v[238:241], v169 offset:23104
	s_nop 6
	v_exp_f32_e32 v0, v0
	s_waitcnt lgkmcnt(3)
	v_mfma_f32_16x16x32_bf16 v[4:7], v[242:245], v[24:27], v[8:11]
	ds_read_b128 v[242:245], v169 offset:25344
	v_exp_f32_e32 v1, v1
	v_exp_f32_e32 v2, v2
	s_waitcnt lgkmcnt(3)
	v_mfma_f32_16x16x32_bf16 v[4:7], v[246:249], v[28:31], v[4:7]
	ds_read_b128 v[246:249], v169 offset:25408
	v_exp_f32_e32 v3, v3
	s_nop 5
	v_exp_f32_e32 v4, v4
	s_waitcnt lgkmcnt(3)
	v_mfma_f32_16x16x32_bf16 v[8:11], v[226:229], v[24:27], v[12:15]
	v_exp_f32_e32 v5, v5
	v_exp_f32_e32 v6, v6
	s_waitcnt lgkmcnt(2)
	v_mfma_f32_16x16x32_bf16 v[8:11], v[238:241], v[28:31], v[8:11]
	v_exp_f32_e32 v7, v7
	s_nop 6
	v_exp_f32_e32 v8, v8
	s_waitcnt lgkmcnt(1)
	v_mfma_f32_16x16x32_bf16 v[12:15], v[242:245], v[24:27], v[222:225]
	v_exp_f32_e32 v9, v9
	v_exp_f32_e32 v10, v10
	s_waitcnt lgkmcnt(0)
	v_mfma_f32_16x16x32_bf16 v[12:15], v[246:249], v[28:31], v[12:15]
	v_exp_f32_e32 v11, v11
	s_nop 6
	v_exp_f32_e32 v12, v12
	v_exp_f32_e32 v13, v13
	v_exp_f32_e32 v14, v14
	v_exp_f32_e32 v15, v15
	s_cbranch_vccnz .LBB0_369
	v_add_f32_e32 v169, 0, v0
	v_add_f32_e32 v169, v1, v169
	v_add_f32_e32 v169, v2, v169
	v_add_f32_e32 v169, v3, v169
	v_add_f32_e32 v169, v169, v4
	v_add_f32_e32 v169, v5, v169
	v_add_f32_e32 v169, v6, v169
	v_add_f32_e32 v169, v7, v169
	v_add_f32_e32 v169, v169, v8
	v_add_f32_e32 v169, v9, v169
	v_add_f32_e32 v169, v10, v169
	v_add_f32_e32 v169, v11, v169
	v_add_f32_e32 v169, v169, v12
	v_add_f32_e32 v169, v13, v169
	v_add_f32_e32 v169, v14, v169
	v_add_f32_e32 v169, v15, v169
	s_mov_b64 s[12:13], 0

; #define LAS __attribute__((address_space(3)))
; template <bool PASSB>
; DI void s5_pass(const int tid, LAS unsigned char* lds, const P& p, int G, int c0) {
;     ...
;             for (int t = 0; t < 16; ++t) {
;                 float bur = 0.f, bui = 0.f;
; #pragma unroll
;                 for (int k = 0; k < 4; ++k) { const f32x4 u = *(const LAS f32x4*)(ubuf + t * 16 + k * 4);
; #pragma unroll
;                     for (int e = 0; e < 4; ++e) { bur += bre[4 * k + e] * u[e]; bui += bim[4 * k + e] * u[e]; } }
;                 const float nr = are * hre - aim * him + bur, ni = are * him + aim * hre + bui; hre = nr; him = ni;
;                 if (PASSB) { hbuf[t * 136 + lane] = f2bf(hre); hbuf[t * 136 + 64 + lane] = f2bf(-him); }
.LBB0_576:
	v_add_u32_e32 v33, s0, v77
	ds_read_b128 v[114:117], v33
	ds_read_b128 v[118:121], v33 offset:16
	ds_read_b128 v[122:125], v33 offset:32
	ds_read_b128 v[126:129], v33 offset:48
	ds_read_b128 v[130:133], v33 offset:64
	ds_read_b128 v[134:137], v33 offset:80
	ds_read_b128 v[138:141], v33 offset:96
	ds_read_b128 v[142:145], v33 offset:112
	ds_read_b128 v[150:153], v33 offset:128
	v_add_u32_e32 v91, v77, v32
	s_waitcnt lgkmcnt(8)
	v_fma_f32 v34, v12, v114, 0
	v_fma_f32 v35, v13, v114, 0
	v_add_u32_e32 v32, 0x880, v32
	v_fma_f32 v34, v38, v115, v34
	v_fma_f32 v35, v39, v115, v35
	ds_read_b128 v[154:157], v33 offset:144
	v_mov_b32_e32 v92, v117
	v_fma_f32 v34, v14, v116, v34
	v_fma_f32 v35, v15, v116, v35
	s_waitcnt lgkmcnt(8)
	v_mov_b32_e32 v94, v121
	v_fma_f32 v34, v72, v92, v34
	v_fma_f32 v35, v73, v92, v35
	v_mul_f32_e64 v92, v36, v75
	v_mul_f32_e64 v93, v37, v75
	v_fma_f32 v34, v8, v118, v34
	v_fma_f32 v35, v9, v118, v35
	v_fma_f32 v34, v70, v119, v34
	v_fma_f32 v35, v71, v119, v35
	ds_read_b128 v[158:161], v33 offset:160
	v_fma_f32 v34, v10, v120, v34
	v_fma_f32 v35, v11, v120, v35
	v_fma_f32 v34, v40, v94, v34
	v_fma_f32 v35, v41, v94, v35
	s_waitcnt lgkmcnt(8)
	v_mov_b32_e32 v94, v125
	v_fma_f32 v34, v4, v122, v34
	v_fma_f32 v35, v5, v122, v35
	v_fma_f32 v34, v42, v123, v34
	v_fma_f32 v35, v43, v123, v35
	ds_read_b128 v[162:165], v33 offset:176
	v_fma_f32 v34, v6, v124, v34
	v_fma_f32 v35, v7, v124, v35
	v_fma_f32 v34, v44, v94, v34
	v_fma_f32 v35, v45, v94, v35
	s_waitcnt lgkmcnt(8)
	v_mov_b32_e32 v94, v129
	v_fma_f32 v34, v0, v126, v34
	v_fma_f32 v35, v1, v126, v35
	v_fma_f32 v34, v46, v127, v34
	v_fma_f32 v35, v47, v127, v35
	v_fma_f32 v34, v2, v128, v34
	v_fma_f32 v35, v3, v128, v35
	v_fma_f32 v34, v68, v94, v34
	v_fma_f32 v35, v69, v94, v35
	v_fma_f32 v94, v60, v74, -v92
	v_fma_f32 v95, v61, v75, -v93
	v_fma_f32 v75, v61, v74, v93
	v_fma_f32 v74, v60, v74, v92
	v_mov_b32_e32 v95, v75
	v_add_f32_e64 v34, v94, v34
	v_add_f32_e64 v35, v95, v35
	v_cvt_pk_bf16_f32 v74, v34, s0
	ds_write_b16 v91, v74
	ds_read_b128 v[114:117], v33 offset:192
	v_cvt_pk_bf16_f32 v74, -v35, s0
	ds_write_b16 v91, v74 offset:128
	s_waitcnt lgkmcnt(10)
	v_fma_f32 v74, v12, v130, 0
	v_fma_f32 v75, v13, v130, 0
	v_fma_f32 v74, v38, v131, v74
	v_fma_f32 v75, v39, v131, v75
	ds_read_b128 v[118:121], v33 offset:208
	v_mov_b32_e32 v92, v133
	v_fma_f32 v74, v14, v132, v74
	v_fma_f32 v75, v15, v132, v75
	s_waitcnt lgkmcnt(10)
	v_mov_b32_e32 v94, v137
	v_fma_f32 v74, v72, v92, v74
	v_fma_f32 v75, v73, v92, v75
	v_mul_f32_e64 v92, v36, v35
	v_mul_f32_e64 v93, v37, v35
	v_fma_f32 v74, v8, v134, v74
	v_fma_f32 v75, v9, v134, v75
	v_fma_f32 v74, v70, v135, v74
	v_fma_f32 v75, v71, v135, v75
	ds_read_b128 v[122:125], v33 offset:224
	v_fma_f32 v74, v10, v136, v74
	v_fma_f32 v75, v11, v136, v75
	v_fma_f32 v74, v40, v94, v74
	v_fma_f32 v75, v41, v94, v75
	s_waitcnt lgkmcnt(10)
	v_mov_b32_e32 v94, v141
	v_fma_f32 v74, v4, v138, v74
	v_fma_f32 v75, v5, v138, v75
	v_fma_f32 v74, v42, v139, v74
	v_fma_f32 v75, v43, v139, v75
	ds_read_b128 v[126:129], v33 offset:240
	v_fma_f32 v74, v6, v140, v74
	v_fma_f32 v75, v7, v140, v75
	v_fma_f32 v74, v44, v94, v74
	v_fma_f32 v75, v45, v94, v75
	s_waitcnt lgkmcnt(10)
	v_mov_b32_e32 v94, v145
	v_fma_f32 v74, v0, v142, v74
	v_fma_f32 v75, v1, v142, v75
	v_fma_f32 v74, v46, v143, v74
	v_fma_f32 v75, v47, v143, v75
	v_fma_f32 v74, v2, v144, v74
	v_fma_f32 v75, v3, v144, v75
	v_fma_f32 v74, v68, v94, v74
	v_fma_f32 v75, v69, v94, v75
	v_fma_f32 v94, v60, v34, -v92
	v_fma_f32 v95, v61, v35, -v93
	v_fma_f32 v35, v61, v34, v93
	v_fma_f32 v34, v60, v34, v92
	v_mov_b32_e32 v95, v35
	v_add_f32_e64 v34, v94, v74
	v_add_f32_e64 v35, v95, v75
	v_cvt_pk_bf16_f32 v74, v34, s0
	ds_write_b16 v91, v74 offset:272
	ds_read_b128 v[130:133], v33 offset:256
	v_cvt_pk_bf16_f32 v74, -v35, s0
	ds_write_b16 v91, v74 offset:400
	s_waitcnt lgkmcnt(12)
	v_fma_f32 v74, v12, v150, 0
	v_fma_f32 v75, v13, v150, 0
	v_fma_f32 v74, v38, v151, v74
	v_fma_f32 v75, v39, v151, v75
	ds_read_b128 v[134:137], v33 offset:272
	v_mov_b32_e32 v92, v153
	v_fma_f32 v74, v14, v152, v74
	v_fma_f32 v75, v15, v152, v75
	s_waitcnt lgkmcnt(12)
	v_mov_b32_e32 v94, v157
	v_fma_f32 v74, v72, v92, v74
	v_fma_f32 v75, v73, v92, v75
	v_mul_f32_e64 v92, v36, v35
	v_mul_f32_e64 v93, v37, v35
	v_fma_f32 v74, v8, v154, v74
	v_fma_f32 v75, v9, v154, v75
	v_fma_f32 v74, v70, v155, v74
	v_fma_f32 v75, v71, v155, v75
	ds_read_b128 v[138:141], v33 offset:288
	v_fma_f32 v74, v10, v156, v74
	v_fma_f32 v75, v11, v156, v75
	v_fma_f32 v74, v40, v94, v74
	v_fma_f32 v75, v41, v94, v75
	s_waitcnt lgkmcnt(12)
	v_mov_b32_e32 v94, v161
	v_fma_f32 v74, v4, v158, v74
	v_fma_f32 v75, v5, v158, v75
	v_fma_f32 v74, v42, v159, v74
	v_fma_f32 v75, v43, v159, v75
	ds_read_b128 v[142:145], v33 offset:304
	v_fma_f32 v74, v6, v160, v74
	v_fma_f32 v75, v7, v160, v75
	v_fma_f32 v74, v44, v94, v74
	v_fma_f32 v75, v45, v94, v75
	s_waitcnt lgkmcnt(12)
	v_mov_b32_e32 v94, v165
	v_fma_f32 v74, v0, v162, v74
	v_fma_f32 v75, v1, v162, v75
	v_fma_f32 v74, v46, v163, v74
	v_fma_f32 v75, v47, v163, v75
	v_fma_f32 v74, v2, v164, v74
	v_fma_f32 v75, v3, v164, v75
	v_fma_f32 v74, v68, v94, v74
	v_fma_f32 v75, v69, v94, v75
	v_fma_f32 v94, v60, v34, -v92
	v_fma_f32 v95, v61, v35, -v93
	v_fma_f32 v35, v61, v34, v93
	v_fma_f32 v34, v60, v34, v92
	v_mov_b32_e32 v95, v35
	v_add_f32_e64 v34, v94, v74
	v_add_f32_e64 v35, v95, v75
	v_cvt_pk_bf16_f32 v74, v34, s0
	ds_write_b16 v91, v74 offset:544
	ds_read_b128 v[150:153], v33 offset:320
	v_cvt_pk_bf16_f32 v74, -v35, s0
	ds_write_b16 v91, v74 offset:672
	s_waitcnt lgkmcnt(13)
; #define LAS __attribute__((address_space(3)))
; template <bool PASSB>
; DI void s5_pass(const int tid, LAS unsigned char* lds, const P& p, int G, int c0) {
;     ...
;             for (int t = 0; t < 16; ++t) {
;                 float bur = 0.f, bui = 0.f;
; #pragma unroll
;                 for (int k = 0; k < 4; ++k) { const f32x4 u = *(const LAS f32x4*)(ubuf + t * 16 + k * 4);
; #pragma unroll
;                     for (int e = 0; e < 4; ++e) { bur += bre[4 * k + e] * u[e]; bui += bim[4 * k + e] * u[e]; } }
;                 const float nr = are * hre - aim * him + bur, ni = are * him + aim * hre + bui; hre = nr; him = ni;
;                 if (PASSB) { hbuf[t * 136 + lane] = f2bf(hre); hbuf[t * 136 + 64 + lane] = f2bf(-him); }
	v_fma_f32 v74, v12, v114, 0
	v_fma_f32 v75, v13, v114, 0
	v_fma_f32 v74, v38, v115, v74
	v_fma_f32 v75, v39, v115, v75
	ds_read_b128 v[154:157], v33 offset:336
	v_mov_b32_e32 v92, v117
	v_fma_f32 v74, v14, v116, v74
	v_fma_f32 v75, v15, v116, v75
	s_waitcnt lgkmcnt(12)
	v_mov_b32_e32 v94, v121
	v_fma_f32 v74, v72, v92, v74
	v_fma_f32 v75, v73, v92, v75
	v_mul_f32_e64 v92, v36, v35
	v_mul_f32_e64 v93, v37, v35
	v_fma_f32 v74, v8, v118, v74
	v_fma_f32 v75, v9, v118, v75
	v_fma_f32 v74, v70, v119, v74
	v_fma_f32 v75, v71, v119, v75
	ds_read_b128 v[158:161], v33 offset:352
	v_fma_f32 v74, v10, v120, v74
	v_fma_f32 v75, v11, v120, v75
	v_fma_f32 v74, v40, v94, v74
	v_fma_f32 v75, v41, v94, v75
	s_waitcnt lgkmcnt(12)
	v_mov_b32_e32 v94, v125
	v_fma_f32 v74, v4, v122, v74
	v_fma_f32 v75, v5, v122, v75
	v_fma_f32 v74, v42, v123, v74
	v_fma_f32 v75, v43, v123, v75
	ds_read_b128 v[162:165], v33 offset:368
	v_fma_f32 v74, v6, v124, v74
	v_fma_f32 v75, v7, v124, v75
	v_fma_f32 v74, v44, v94, v74
	v_fma_f32 v75, v45, v94, v75
	s_waitcnt lgkmcnt(12)
	v_mov_b32_e32 v94, v129
	v_fma_f32 v74, v0, v126, v74
	v_fma_f32 v75, v1, v126, v75
	v_fma_f32 v74, v46, v127, v74
	v_fma_f32 v75, v47, v127, v75
	v_fma_f32 v74, v2, v128, v74
	v_fma_f32 v75, v3, v128, v75
	v_fma_f32 v74, v68, v94, v74
	v_fma_f32 v75, v69, v94, v75
	v_fma_f32 v94, v60, v34, -v92
	v_fma_f32 v95, v61, v35, -v93
	v_fma_f32 v35, v61, v34, v93
	v_fma_f32 v34, v60, v34, v92
	v_mov_b32_e32 v95, v35
	v_add_f32_e64 v34, v94, v74
	v_add_f32_e64 v35, v95, v75
	v_cvt_pk_bf16_f32 v74, v34, s0
	ds_write_b16 v91, v74 offset:816
	ds_read_b128 v[114:117], v33 offset:384
	v_cvt_pk_bf16_f32 v74, -v35, s0
	ds_write_b16 v91, v74 offset:944
	s_waitcnt lgkmcnt(13)
	v_fma_f32 v74, v12, v130, 0
	v_fma_f32 v75, v13, v130, 0
	v_fma_f32 v74, v38, v131, v74
	v_fma_f32 v75, v39, v131, v75
	ds_read_b128 v[118:121], v33 offset:400
	v_mov_b32_e32 v92, v133
	v_fma_f32 v74, v14, v132, v74
	v_fma_f32 v75, v15, v132, v75
	s_waitcnt lgkmcnt(12)
	v_mov_b32_e32 v94, v137
	v_fma_f32 v74, v72, v92, v74
	v_fma_f32 v75, v73, v92, v75
	v_mul_f32_e64 v92, v36, v35
	v_mul_f32_e64 v93, v37, v35
	v_fma_f32 v74, v8, v134, v74
	v_fma_f32 v75, v9, v134, v75
	v_fma_f32 v74, v70, v135, v74
	v_fma_f32 v75, v71, v135, v75
	ds_read_b128 v[122:125], v33 offset:416
	v_fma_f32 v74, v10, v136, v74
	v_fma_f32 v75, v11, v136, v75
	v_fma_f32 v74, v40, v94, v74
	v_fma_f32 v75, v41, v94, v75
	s_waitcnt lgkmcnt(12)
	v_mov_b32_e32 v94, v141
	v_fma_f32 v74, v4, v138, v74
	v_fma_f32 v75, v5, v138, v75
	v_fma_f32 v74, v42, v139, v74
	v_fma_f32 v75, v43, v139, v75
	ds_read_b128 v[126:129], v33 offset:432
	v_fma_f32 v74, v6, v140, v74
	v_fma_f32 v75, v7, v140, v75
	v_fma_f32 v74, v44, v94, v74
	v_fma_f32 v75, v45, v94, v75
	s_waitcnt lgkmcnt(12)
	v_mov_b32_e32 v94, v145
	v_fma_f32 v74, v0, v142, v74
	v_fma_f32 v75, v1, v142, v75
	v_fma_f32 v74, v46, v143, v74
	v_fma_f32 v75, v47, v143, v75
	v_fma_f32 v74, v2, v144, v74
	v_fma_f32 v75, v3, v144, v75
	v_fma_f32 v74, v68, v94, v74
	v_fma_f32 v75, v69, v94, v75
	v_fma_f32 v94, v60, v34, -v92
	v_fma_f32 v95, v61, v35, -v93
	v_fma_f32 v35, v61, v34, v93
	v_fma_f32 v34, v60, v34, v92
	v_mov_b32_e32 v95, v35
	v_add_f32_e64 v34, v94, v74
	v_add_f32_e64 v35, v95, v75
	v_cvt_pk_bf16_f32 v74, v34, s0
	ds_write_b16 v91, v74 offset:1088
	ds_read_b128 v[130:133], v33 offset:448
	v_cvt_pk_bf16_f32 v74, -v35, s0
	ds_write_b16 v91, v74 offset:1216
	s_waitcnt lgkmcnt(13)
	v_fma_f32 v74, v12, v150, 0
	v_fma_f32 v75, v13, v150, 0
	v_fma_f32 v74, v38, v151, v74
	v_fma_f32 v75, v39, v151, v75
	ds_read_b128 v[134:137], v33 offset:464
	v_mov_b32_e32 v92, v153
	v_fma_f32 v74, v14, v152, v74
	v_fma_f32 v75, v15, v152, v75
	s_waitcnt lgkmcnt(12)
	v_mov_b32_e32 v94, v157
	v_fma_f32 v74, v72, v92, v74
	v_fma_f32 v75, v73, v92, v75
	v_mul_f32_e64 v92, v36, v35
	v_mul_f32_e64 v93, v37, v35
	v_fma_f32 v74, v8, v154, v74
	v_fma_f32 v75, v9, v154, v75
	v_fma_f32 v74, v70, v155, v74
	v_fma_f32 v75, v71, v155, v75
	ds_read_b128 v[138:141], v33 offset:480
	v_fma_f32 v74, v10, v156, v74
	v_fma_f32 v75, v11, v156, v75
	v_fma_f32 v74, v40, v94, v74
	v_fma_f32 v75, v41, v94, v75
	s_waitcnt lgkmcnt(12)
	v_mov_b32_e32 v94, v161
	v_fma_f32 v74, v4, v158, v74
	v_fma_f32 v75, v5, v158, v75
	v_fma_f32 v74, v42, v159, v74
	v_fma_f32 v75, v43, v159, v75
	ds_read_b128 v[142:145], v33 offset:496
	v_fma_f32 v74, v6, v160, v74
	v_fma_f32 v75, v7, v160, v75
	v_fma_f32 v74, v44, v94, v74
	v_fma_f32 v75, v45, v94, v75
	s_waitcnt lgkmcnt(12)
	v_mov_b32_e32 v94, v165
	v_fma_f32 v74, v0, v162, v74
	v_fma_f32 v75, v1, v162, v75
	v_fma_f32 v74, v46, v163, v74
	v_fma_f32 v75, v47, v163, v75
	v_fma_f32 v74, v2, v164, v74
	v_fma_f32 v75, v3, v164, v75
	v_fma_f32 v74, v68, v94, v74
	v_fma_f32 v75, v69, v94, v75
	v_fma_f32 v94, v60, v34, -v92
	v_fma_f32 v95, v61, v35, -v93
	v_fma_f32 v35, v61, v34, v93
	v_fma_f32 v34, v60, v34, v92
	v_mov_b32_e32 v95, v35
	v_add_f32_e64 v34, v94, v74
	v_add_f32_e64 v35, v95, v75
	v_cvt_pk_bf16_f32 v74, v34, s0
	ds_write_b16 v91, v74 offset:1360
	v_cvt_pk_bf16_f32 v74, -v35, s0
	ds_write_b16 v91, v74 offset:1488
	s_waitcnt lgkmcnt(12)
	v_fma_f32 v74, v12, v114, 0
	v_fma_f32 v75, v13, v114, 0
	v_fma_f32 v74, v38, v115, v74
	v_fma_f32 v75, v39, v115, v75
	v_mov_b32_e32 v92, v117
	v_fma_f32 v74, v14, v116, v74
	v_fma_f32 v75, v15, v116, v75
	s_waitcnt lgkmcnt(10)
	v_mov_b32_e32 v94, v121
	v_fma_f32 v74, v72, v92, v74
	v_fma_f32 v75, v73, v92, v75
	v_mul_f32_e64 v92, v36, v35
	v_mul_f32_e64 v93, v37, v35
	v_fma_f32 v74, v8, v118, v74
	v_fma_f32 v75, v9, v118, v75
	v_fma_f32 v74, v70, v119, v74
	v_fma_f32 v75, v71, v119, v75
	v_fma_f32 v74, v10, v120, v74
	v_fma_f32 v75, v11, v120, v75
	v_fma_f32 v74, v40, v94, v74
	v_fma_f32 v75, v41, v94, v75
	s_waitcnt lgkmcnt(9)
; #define LAS __attribute__((address_space(3)))
; template <bool PASSB>
; DI void s5_pass(const int tid, LAS unsigned char* lds, const P& p, int G, int c0) {
;     ...
;             for (int t = 0; t < 16; ++t) {
;                 float bur = 0.f, bui = 0.f;
; #pragma unroll
;                 for (int k = 0; k < 4; ++k) { const f32x4 u = *(const LAS f32x4*)(ubuf + t * 16 + k * 4);
; #pragma unroll
;                     for (int e = 0; e < 4; ++e) { bur += bre[4 * k + e] * u[e]; bui += bim[4 * k + e] * u[e]; } }
;                 const float nr = are * hre - aim * him + bur, ni = are * him + aim * hre + bui; hre = nr; him = ni;
;                 if (PASSB) { hbuf[t * 136 + lane] = f2bf(hre); hbuf[t * 136 + 64 + lane] = f2bf(-him); }
	v_mov_b32_e32 v94, v125
	v_fma_f32 v74, v4, v122, v74
	v_fma_f32 v75, v5, v122, v75
	v_fma_f32 v74, v42, v123, v74
	v_fma_f32 v75, v43, v123, v75
	v_fma_f32 v74, v6, v124, v74
	v_fma_f32 v75, v7, v124, v75
	v_fma_f32 v74, v44, v94, v74
	v_fma_f32 v75, v45, v94, v75
	s_waitcnt lgkmcnt(8)
	v_mov_b32_e32 v94, v129
	v_fma_f32 v74, v0, v126, v74
	v_fma_f32 v75, v1, v126, v75
	v_fma_f32 v74, v46, v127, v74
	v_fma_f32 v75, v47, v127, v75
	v_fma_f32 v74, v2, v128, v74
	v_fma_f32 v75, v3, v128, v75
	v_fma_f32 v74, v68, v94, v74
	v_fma_f32 v75, v69, v94, v75
	v_fma_f32 v94, v60, v34, -v92
	v_fma_f32 v95, v61, v35, -v93
	v_fma_f32 v35, v61, v34, v93
	v_fma_f32 v34, v60, v34, v92
	v_mov_b32_e32 v95, v35
	v_add_f32_e64 v34, v94, v74
	v_add_f32_e64 v35, v95, v75
	v_cvt_pk_bf16_f32 v74, v34, s0
	ds_write_b16 v91, v74 offset:1632
	v_cvt_pk_bf16_f32 v74, -v35, s0
	ds_write_b16 v91, v74 offset:1760
	s_waitcnt lgkmcnt(8)
	v_fma_f32 v74, v12, v130, 0
	v_fma_f32 v75, v13, v130, 0
	v_fma_f32 v74, v38, v131, v74
	v_fma_f32 v75, v39, v131, v75
	v_mov_b32_e32 v92, v133
	v_fma_f32 v74, v14, v132, v74
	v_fma_f32 v75, v15, v132, v75
	s_waitcnt lgkmcnt(6)
	v_mov_b32_e32 v94, v137
	v_fma_f32 v74, v72, v92, v74
	v_fma_f32 v75, v73, v92, v75
	v_mul_f32_e64 v92, v36, v35
	v_mul_f32_e64 v93, v37, v35
	v_fma_f32 v74, v8, v134, v74
	v_fma_f32 v75, v9, v134, v75
	v_fma_f32 v74, v70, v135, v74
	v_fma_f32 v75, v71, v135, v75
	v_fma_f32 v74, v10, v136, v74
	v_fma_f32 v75, v11, v136, v75
	v_fma_f32 v74, v40, v94, v74
	v_fma_f32 v75, v41, v94, v75
	s_waitcnt lgkmcnt(5)
	v_mov_b32_e32 v94, v141
	v_fma_f32 v74, v4, v138, v74
	v_fma_f32 v75, v5, v138, v75
	v_fma_f32 v74, v42, v139, v74
	v_fma_f32 v75, v43, v139, v75
	v_fma_f32 v74, v6, v140, v74
	v_fma_f32 v75, v7, v140, v75
	v_fma_f32 v74, v44, v94, v74
	v_fma_f32 v75, v45, v94, v75
	s_waitcnt lgkmcnt(4)
	v_mov_b32_e32 v94, v145
	v_fma_f32 v74, v0, v142, v74
	v_fma_f32 v75, v1, v142, v75
	v_fma_f32 v74, v46, v143, v74
	v_fma_f32 v75, v47, v143, v75
	v_fma_f32 v74, v2, v144, v74
	v_fma_f32 v75, v3, v144, v75
	v_fma_f32 v74, v68, v94, v74
	v_fma_f32 v75, v69, v94, v75
	v_fma_f32 v94, v60, v34, -v92
	v_fma_f32 v95, v61, v35, -v93
	v_fma_f32 v35, v61, v34, v93
	v_fma_f32 v34, v60, v34, v92
	v_mov_b32_e32 v95, v35
	v_add_f32_e64 v74, v94, v74
	v_add_f32_e64 v75, v95, v75
	v_cvt_pk_bf16_f32 v33, v74, s0
	ds_write_b16 v91, v33 offset:1904
	v_cvt_pk_bf16_f32 v33, -v75, s0
	s_addk_i32 s0, 0x200
	s_cmpk_lg_i32 s0, 0x400
	ds_write_b16 v91, v33 offset:2032
	s_cbranch_scc1 .LBB0_576
; #define LAS __attribute__((address_space(3)))
; DI float gelu_tanh(float x) { float u = 0.7978845608028654f * (x + 0.044715f * x * x * x); float e = __expf(2.f * u); float th = 1.f - 2.f / (e + 1.f); return 0.5f * x * (1.f + th); }
; DI f32x4 mfma16(bf16x8 a, bf16x8 b, f32x4 c) { return __builtin_amdgcn_mfma_f32_16x16x32_bf16(a, b, c, 0, 0, 0); }
; DI void lds_wait() { asm volatile("s_waitcnt lgkmcnt(0)" ::: "memory"); }
; template <bool PASSB>
; DI void s5_pass(const int tid, LAS unsigned char* lds, const P& p, int G, int c0) {
;     ...
;             if (PASSB) {
;                 lds_wait();
;                 f32x4 acc = (f32x4){0.f, 0.f, 0.f, 0.f};
; #pragma unroll
;                 for (int ks = 0; ks < 4; ++ks) { const bf16x8 a = *(const LAS bf16x8*)(hbuf + fr * 136 + ks * 32 + fq * 8); acc = mfma16(a, cf[ks], acc); }
; #pragma unroll
;                 for (int j = 0; j < 4; ++j) { const int tk = fq * 4 + j; const float y = acc[j] + dsk * ubuf[tk * 16 + fr];
;                     zs5[(tokbase + tile * 16 + tk) * 256 + g * 16 + fr] = f2bf(gelu_tanh(y)); }
;             }
;             lds_wait();
;         }
;         if (!PASSB) { float* he = hend + (((size_t)(b * 16 + g) * 8 + seg) * 64 + lane) * 2; he[0] = hre; he[1] = him; }
	s_waitcnt lgkmcnt(0)
	v_add_u32_e32 v91, v80, v48
	ds_read_b128 v[32:35], v91 offset:1024
	ds_read_b128 v[92:95], v91 offset:1088
	s_lshl_b32 s0, s8, 4
	s_add_i32 s8, s8, 1
	s_cmp_eq_u32 s8, 16
	s_waitcnt vmcnt(4) lgkmcnt(1)
	v_mfma_f32_16x16x32_bf16 v[32:35], v[32:35], v[16:19], 0
	s_waitcnt vmcnt(3) lgkmcnt(0)
	v_mfma_f32_16x16x32_bf16 v[32:35], v[92:95], v[20:23], v[32:35]
	ds_read_b128 v[92:95], v91 offset:1152
	s_waitcnt vmcnt(2) lgkmcnt(0)
	v_mfma_f32_16x16x32_bf16 v[32:35], v[92:95], v[24:27], v[32:35]
	ds_read_b128 v[92:95], v91 offset:1216
	ds_read_b32 v91, v86
	s_waitcnt vmcnt(1) lgkmcnt(1)
	v_mfma_f32_16x16x32_bf16 v[32:35], v[92:95], v[28:31], v[32:35]
	s_waitcnt vmcnt(0) lgkmcnt(0)
	s_nop 6
	v_fma_f32 v32, v90, v91, v32
	v_mul_f32_e32 v91, 0x3d372713, v32
	v_mul_f32_e32 v91, v32, v91
	v_fma_f32 v91, v32, v91, v32
	v_mul_f32_e32 v91, 0x3f4c422a, v91
	v_add_f32_e32 v91, v91, v91
	v_mul_f32_e32 v91, 0x3fb8aa3b, v91
	v_exp_f32_e32 v91, v91
	v_mul_f32_e32 v32, 0.5, v32
	v_add_f32_e32 v91, 1.0, v91
	v_div_scale_f32 v92, s[10:11], v91, v91, 2.0
	v_rcp_f32_e32 v93, v92
	s_nop 0
	v_fma_f32 v94, -v92, v93, 1.0
	v_fmac_f32_e32 v93, v94, v93
	v_div_scale_f32 v94, vcc, 2.0, v91, 2.0
	v_mul_f32_e32 v95, v94, v93
	v_fma_f32 v96, -v92, v95, v94
	v_fmac_f32_e32 v95, v96, v93
	v_fma_f32 v92, -v92, v95, v94
	v_div_fmas_f32 v92, v92, v93, v95
	v_div_fixup_f32 v91, v92, v91, 2.0
	v_sub_f32_e32 v91, 1.0, v91
	v_add_f32_e32 v91, 1.0, v91
	v_or3_b32 v92, s0, v81, v62
	v_mov_b32_e32 v93, v63
	v_mul_f32_e32 v32, v32, v91
	v_lshlrev_b64 v[92:93], 9, v[92:93]
	v_cvt_pk_bf16_f32 v32, v32, s0
	v_lshl_add_u64 v[92:93], v[66:67], 0, v[92:93]
	global_store_short v[92:93], v32, off
	ds_read_b32 v32, v87
	s_waitcnt lgkmcnt(0)
	v_fma_f32 v32, v90, v32, v33
	v_mul_f32_e32 v33, 0x3d372713, v32
	v_mul_f32_e32 v33, v32, v33
	v_fma_f32 v33, v32, v33, v32
	v_mul_f32_e32 v33, 0x3f4c422a, v33
	v_add_f32_e32 v33, v33, v33
	v_mul_f32_e32 v33, 0x3fb8aa3b, v33
	v_exp_f32_e32 v33, v33
	v_mul_f32_e32 v32, 0.5, v32
	v_add_f32_e32 v33, 1.0, v33
	v_div_scale_f32 v91, s[10:11], v33, v33, 2.0
	v_rcp_f32_e32 v92, v91
	s_nop 0
	v_fma_f32 v93, -v91, v92, 1.0
	v_fmac_f32_e32 v92, v93, v92
	v_div_scale_f32 v93, vcc, 2.0, v33, 2.0
	v_mul_f32_e32 v94, v93, v92
	v_fma_f32 v95, -v91, v94, v93
	v_fmac_f32_e32 v94, v95, v92
	v_fma_f32 v91, -v91, v94, v93
	v_div_fmas_f32 v91, v91, v92, v94
	v_div_fixup_f32 v33, v91, v33, 2.0
	v_sub_f32_e32 v33, 1.0, v33
	v_add_f32_e32 v33, 1.0, v33
	v_mul_f32_e32 v32, v32, v33
	v_cvt_pk_bf16_f32 v91, v32, s0
	v_or3_b32 v32, s0, v82, v62
	v_mov_b32_e32 v33, v63
	v_lshlrev_b64 v[32:33], 9, v[32:33]
	v_lshl_add_u64 v[32:33], v[66:67], 0, v[32:33]
	global_store_short v[32:33], v91, off
	ds_read_b32 v32, v88
	s_waitcnt lgkmcnt(0)
	v_fma_f32 v32, v90, v32, v34
	v_mul_f32_e32 v33, 0x3d372713, v32
	v_mul_f32_e32 v33, v32, v33
	v_fma_f32 v33, v32, v33, v32
	v_mul_f32_e32 v33, 0x3f4c422a, v33
	v_add_f32_e32 v33, v33, v33
	v_mul_f32_e32 v33, 0x3fb8aa3b, v33
	v_exp_f32_e32 v33, v33
	v_mul_f32_e32 v32, 0.5, v32
	v_add_f32_e32 v33, 1.0, v33
	v_div_scale_f32 v34, s[10:11], v33, v33, 2.0
	v_rcp_f32_e32 v91, v34
	s_nop 0
	v_fma_f32 v92, -v34, v91, 1.0
	v_fmac_f32_e32 v91, v92, v91
	v_div_scale_f32 v92, vcc, 2.0, v33, 2.0
	v_mul_f32_e32 v93, v92, v91
	v_fma_f32 v94, -v34, v93, v92
	v_fmac_f32_e32 v93, v94, v91
	v_fma_f32 v34, -v34, v93, v92
	v_div_fmas_f32 v34, v34, v91, v93
	v_div_fixup_f32 v33, v34, v33, 2.0
	v_sub_f32_e32 v33, 1.0, v33
	v_add_f32_e32 v33, 1.0, v33
	v_mul_f32_e32 v32, v32, v33
	v_cvt_pk_bf16_f32 v34, v32, s0
	v_or3_b32 v32, s0, v83, v62
	v_mov_b32_e32 v33, v63
	v_lshlrev_b64 v[32:33], 9, v[32:33]
	v_lshl_add_u64 v[32:33], v[66:67], 0, v[32:33]
	global_store_short v[32:33], v34, off
	ds_read_b32 v32, v89
	s_waitcnt lgkmcnt(0)
	v_fmac_f32_e32 v35, v90, v32
	v_mul_f32_e32 v32, 0x3d372713, v35
	v_mul_f32_e32 v32, v35, v32
	v_fma_f32 v32, v35, v32, v35
	v_mul_f32_e32 v32, 0x3f4c422a, v32
	v_add_f32_e32 v32, v32, v32
	v_mul_f32_e32 v32, 0x3fb8aa3b, v32
	v_exp_f32_e32 v32, v32
	s_nop 0
	v_add_f32_e32 v32, 1.0, v32
	v_div_scale_f32 v33, s[10:11], v32, v32, 2.0
	v_rcp_f32_e32 v34, v33
	s_nop 0
	v_fma_f32 v91, -v33, v34, 1.0
	v_fmac_f32_e32 v34, v91, v34
	v_div_scale_f32 v91, vcc, 2.0, v32, 2.0
	v_mul_f32_e32 v92, v91, v34
	v_fma_f32 v93, -v33, v92, v91
	v_fmac_f32_e32 v92, v93, v34
	v_fma_f32 v33, -v33, v92, v91
	v_div_fmas_f32 v33, v33, v34, v92
	v_div_fixup_f32 v32, v33, v32, 2.0
	v_sub_f32_e32 v32, 1.0, v32
	v_mul_f32_e32 v33, 0.5, v35
	v_add_f32_e32 v32, 1.0, v32
	v_mul_f32_e32 v32, v33, v32
	v_cvt_pk_bf16_f32 v34, v32, s0
	v_or3_b32 v32, s0, v84, v62
	v_mov_b32_e32 v33, v63
	v_lshlrev_b64 v[32:33], 9, v[32:33]
	v_lshl_add_u64 v[32:33], v[66:67], 0, v[32:33]
	global_store_short v[32:33], v34, off
	s_waitcnt lgkmcnt(0)
	s_cbranch_scc0 .LBB0_573
	v_readlane_b32 s0, v253, 16
	s_add_i32 s12, s12, s0
	s_cmpk_gt_i32 s12, 0x1ff
	v_readlane_b32 s1, v253, 17
	s_cbranch_scc0 .LBB0_568
	s_mov_b32 s64, s13
	s_mov_b32 s67, s26
	s_mov_b32 s66, s28

; #define LAS __attribute__((address_space(3)))
; template <bool PASSB>
; DI void s5_pass(const int tid, LAS unsigned char* lds, const P& p, int G, int c0) {
;     ...
;             for (int t = 0; t < 16; ++t) {
;                 float bur = 0.f, bui = 0.f;
; #pragma unroll
;                 for (int k = 0; k < 4; ++k) { const f32x4 u = *(const LAS f32x4*)(ubuf + t * 16 + k * 4);
; #pragma unroll
;                     for (int e = 0; e < 4; ++e) { bur += bre[4 * k + e] * u[e]; bui += bim[4 * k + e] * u[e]; } }
;                 const float nr = are * hre - aim * him + bur, ni = are * him + aim * hre + bui; hre = nr; him = ni;
.LBB0_588:
	v_add_u32_e32 v25, s0, v51
	ds_read_b128 v[72:75], v25
	ds_read_b128 v[76:79], v25 offset:16
	ds_read_b128 v[80:83], v25 offset:32
	ds_read_b128 v[84:87], v25 offset:48
	ds_read_b128 v[88:91], v25 offset:64
	ds_read_b128 v[92:95], v25 offset:80
	ds_read_b128 v[96:99], v25 offset:96
	ds_read_b128 v[100:103], v25 offset:112
	ds_read_b128 v[104:107], v25 offset:128
	ds_read_b128 v[108:111], v25 offset:144
	s_addk_i32 s0, 0x200
	s_waitcnt lgkmcnt(9)
	v_fma_f32 v70, v12, v72, 0
	v_fma_f32 v71, v13, v72, 0
	s_cmpk_lg_i32 s0, 0x400
	v_fma_f32 v54, v44, v73, v70
	v_fma_f32 v55, v45, v73, v71
	ds_read_b128 v[112:115], v25 offset:160
	v_fma_f32 v54, v14, v74, v54
	v_fma_f32 v55, v15, v74, v55
	v_mov_b32_e32 v56, v75
	v_fma_f32 v54, v42, v56, v54
	v_fma_f32 v55, v43, v56, v55
	v_mov_b32_e32 v56, v49
	s_waitcnt lgkmcnt(9)
	v_fma_f32 v54, v8, v76, v54
	v_fma_f32 v55, v9, v76, v55
	ds_read_b128 v[116:119], v25 offset:176
	v_mul_f32_e64 v57, v47, v56
	v_mul_f32_e64 v56, v46, v56
	v_fma_f32 v54, v40, v77, v54
	v_fma_f32 v55, v41, v77, v55
	v_mov_b32_e32 v58, v79
	v_fma_f32 v54, v10, v78, v54
	v_fma_f32 v55, v11, v78, v55
	v_fma_f32 v54, v38, v58, v54
	v_fma_f32 v55, v39, v58, v55
	s_waitcnt lgkmcnt(9)
	v_mov_b32_e32 v58, v83
	v_fma_f32 v54, v4, v80, v54
	v_fma_f32 v55, v5, v80, v55
	v_fma_f32 v54, v36, v81, v54
	v_fma_f32 v55, v37, v81, v55
	v_fma_f32 v54, v6, v82, v54
	v_fma_f32 v55, v7, v82, v55
	v_fma_f32 v54, v34, v58, v54
	v_fma_f32 v55, v35, v58, v55
	ds_read_b128 v[72:75], v25 offset:192
	s_waitcnt lgkmcnt(9)
	v_mov_b32_e32 v58, v87
	v_fma_f32 v54, v0, v84, v54
	v_fma_f32 v55, v1, v84, v55
	v_fma_f32 v54, v32, v85, v54
	v_fma_f32 v55, v33, v85, v55
	v_fma_f32 v54, v2, v86, v54
	v_fma_f32 v55, v3, v86, v55
	v_fma_f32 v54, v30, v58, v54
	v_fma_f32 v55, v31, v58, v55
	ds_read_b128 v[76:79], v25 offset:208
	v_fma_f32 v58, v22, v48, -v56
	v_fma_f32 v59, v23, v49, -v57
	v_fma_f32 v49, v23, v48, v57
	v_fma_f32 v48, v22, v48, v56
	v_mov_b32_e32 v59, v49
	v_add_f32_e64 v48, v58, v54
	v_add_f32_e64 v49, v59, v55
	v_mul_f32_e64 v66, v46, v49
	v_mul_f32_e64 v67, v47, v49
	ds_read_b128 v[80:83], v25 offset:224
	s_waitcnt lgkmcnt(10)
	v_fma_f32 v62, v12, v88, 0
	v_fma_f32 v63, v13, v88, 0
	v_fma_f32 v54, v44, v89, v62
	v_fma_f32 v55, v45, v89, v63
	v_fma_f32 v54, v14, v90, v54
	v_fma_f32 v55, v15, v90, v55
	v_mov_b32_e32 v56, v91
	v_fma_f32 v54, v42, v56, v54
	v_fma_f32 v55, v43, v56, v55
	ds_read_b128 v[84:87], v25 offset:240
	s_waitcnt lgkmcnt(10)
	v_fma_f32 v54, v8, v92, v54
	v_fma_f32 v55, v9, v92, v55
	v_fma_f32 v58, v40, v93, v54
	v_fma_f32 v59, v41, v93, v55
	v_fma_f32 v58, v10, v94, v58
	v_fma_f32 v59, v11, v94, v59
	v_mov_b32_e32 v60, v95
	v_fma_f32 v58, v38, v60, v58
	v_fma_f32 v59, v39, v60, v59
	s_waitcnt lgkmcnt(9)
	v_fma_f32 v58, v4, v96, v58
	v_fma_f32 v59, v5, v96, v59
	v_fma_f32 v54, v36, v97, v58
	v_fma_f32 v55, v37, v97, v59
	v_fma_f32 v54, v6, v98, v54
	v_fma_f32 v55, v7, v98, v55
	v_mov_b32_e32 v56, v99
	v_fma_f32 v54, v34, v56, v54
	v_fma_f32 v55, v35, v56, v55
	ds_read_b128 v[88:91], v25 offset:256
	s_waitcnt lgkmcnt(9)
	v_mov_b32_e32 v56, v103
	v_fma_f32 v54, v0, v100, v54
	v_fma_f32 v55, v1, v100, v55
	v_fma_f32 v54, v32, v101, v54
	v_fma_f32 v55, v33, v101, v55
	v_fma_f32 v54, v2, v102, v54
	v_fma_f32 v55, v3, v102, v55
	v_fma_f32 v54, v30, v56, v54
	v_fma_f32 v55, v31, v56, v55
	ds_read_b128 v[92:95], v25 offset:272
	v_fma_f32 v56, v22, v48, -v66
	v_fma_f32 v57, v23, v49, -v67
	v_fma_f32 v49, v23, v48, v67
	v_fma_f32 v48, v22, v48, v66
	v_mov_b32_e32 v57, v49
	v_add_f32_e64 v48, v56, v54
	v_add_f32_e64 v49, v57, v55
	v_mul_f32_e64 v66, v46, v49
	v_mul_f32_e64 v67, v47, v49
	ds_read_b128 v[96:99], v25 offset:288
	s_waitcnt lgkmcnt(10)
	v_fma_f32 v62, v12, v104, 0
	v_fma_f32 v63, v13, v104, 0
	v_fma_f32 v54, v44, v105, v62
	v_fma_f32 v55, v45, v105, v63
	v_fma_f32 v54, v14, v106, v54
	v_fma_f32 v55, v15, v106, v55
	v_mov_b32_e32 v56, v107
	v_fma_f32 v54, v42, v56, v54
	v_fma_f32 v55, v43, v56, v55
	ds_read_b128 v[100:103], v25 offset:304
	s_waitcnt lgkmcnt(10)
	v_fma_f32 v54, v8, v108, v54
	v_fma_f32 v55, v9, v108, v55
	v_fma_f32 v58, v40, v109, v54
	v_fma_f32 v59, v41, v109, v55
	v_fma_f32 v58, v10, v110, v58
	v_fma_f32 v59, v11, v110, v59
	v_mov_b32_e32 v60, v111
	v_fma_f32 v58, v38, v60, v58
	v_fma_f32 v59, v39, v60, v59
	s_waitcnt lgkmcnt(9)
	v_fma_f32 v58, v4, v112, v58
	v_fma_f32 v59, v5, v112, v59
	v_fma_f32 v54, v36, v113, v58
	v_fma_f32 v55, v37, v113, v59
	v_fma_f32 v54, v6, v114, v54
	v_fma_f32 v55, v7, v114, v55
	v_mov_b32_e32 v56, v115
	v_fma_f32 v54, v34, v56, v54
	v_fma_f32 v55, v35, v56, v55
	ds_read_b128 v[104:107], v25 offset:320
	s_waitcnt lgkmcnt(9)
	v_mov_b32_e32 v56, v119
	v_fma_f32 v54, v0, v116, v54
	v_fma_f32 v55, v1, v116, v55
	v_fma_f32 v54, v32, v117, v54
	v_fma_f32 v55, v33, v117, v55
	v_fma_f32 v54, v2, v118, v54
	v_fma_f32 v55, v3, v118, v55
	v_fma_f32 v54, v30, v56, v54
	v_fma_f32 v55, v31, v56, v55
	ds_read_b128 v[108:111], v25 offset:336
	v_fma_f32 v56, v22, v48, -v66
	v_fma_f32 v57, v23, v49, -v67
	v_fma_f32 v49, v23, v48, v67
	v_fma_f32 v48, v22, v48, v66
	v_mov_b32_e32 v57, v49
	v_add_f32_e64 v48, v56, v54
	v_add_f32_e64 v49, v57, v55
	v_mul_f32_e64 v66, v46, v49
	v_mul_f32_e64 v67, v47, v49
	ds_read_b128 v[112:115], v25 offset:352
	s_waitcnt lgkmcnt(10)
	v_fma_f32 v62, v12, v72, 0
	v_fma_f32 v63, v13, v72, 0
	v_fma_f32 v54, v44, v73, v62
	v_fma_f32 v55, v45, v73, v63
	v_fma_f32 v54, v14, v74, v54
	v_fma_f32 v55, v15, v74, v55
	v_mov_b32_e32 v56, v75
	v_fma_f32 v54, v42, v56, v54
	v_fma_f32 v55, v43, v56, v55
	ds_read_b128 v[116:119], v25 offset:368
	s_waitcnt lgkmcnt(10)
; #define LAS __attribute__((address_space(3)))
; template <bool PASSB>
; DI void s5_pass(const int tid, LAS unsigned char* lds, const P& p, int G, int c0) {
;     ...
;             for (int t = 0; t < 16; ++t) {
;                 float bur = 0.f, bui = 0.f;
; #pragma unroll
;                 for (int k = 0; k < 4; ++k) { const f32x4 u = *(const LAS f32x4*)(ubuf + t * 16 + k * 4);
; #pragma unroll
;                     for (int e = 0; e < 4; ++e) { bur += bre[4 * k + e] * u[e]; bui += bim[4 * k + e] * u[e]; } }
;                 const float nr = are * hre - aim * him + bur, ni = are * him + aim * hre + bui; hre = nr; him = ni;
	v_fma_f32 v54, v8, v76, v54
	v_fma_f32 v55, v9, v76, v55
	v_fma_f32 v58, v40, v77, v54
	v_fma_f32 v59, v41, v77, v55
	v_fma_f32 v58, v10, v78, v58
	v_fma_f32 v59, v11, v78, v59
	v_mov_b32_e32 v60, v79
	v_fma_f32 v58, v38, v60, v58
	v_fma_f32 v59, v39, v60, v59
	s_waitcnt lgkmcnt(9)
	v_fma_f32 v58, v4, v80, v58
	v_fma_f32 v59, v5, v80, v59
	v_fma_f32 v54, v36, v81, v58
	v_fma_f32 v55, v37, v81, v59
	v_fma_f32 v54, v6, v82, v54
	v_fma_f32 v55, v7, v82, v55
	v_mov_b32_e32 v56, v83
	v_fma_f32 v54, v34, v56, v54
	v_fma_f32 v55, v35, v56, v55
	ds_read_b128 v[72:75], v25 offset:384
	s_waitcnt lgkmcnt(9)
	v_mov_b32_e32 v56, v87
	v_fma_f32 v54, v0, v84, v54
	v_fma_f32 v55, v1, v84, v55
	v_fma_f32 v54, v32, v85, v54
	v_fma_f32 v55, v33, v85, v55
	v_fma_f32 v54, v2, v86, v54
	v_fma_f32 v55, v3, v86, v55
	v_fma_f32 v54, v30, v56, v54
	v_fma_f32 v55, v31, v56, v55
	ds_read_b128 v[76:79], v25 offset:400
	v_fma_f32 v56, v22, v48, -v66
	v_fma_f32 v57, v23, v49, -v67
	v_fma_f32 v49, v23, v48, v67
	v_fma_f32 v48, v22, v48, v66
	v_mov_b32_e32 v57, v49
	v_add_f32_e64 v48, v56, v54
	v_add_f32_e64 v49, v57, v55
	v_mul_f32_e64 v66, v46, v49
	v_mul_f32_e64 v67, v47, v49
	ds_read_b128 v[80:83], v25 offset:416
	s_waitcnt lgkmcnt(10)
	v_fma_f32 v62, v12, v88, 0
	v_fma_f32 v63, v13, v88, 0
	v_fma_f32 v54, v44, v89, v62
	v_fma_f32 v55, v45, v89, v63
	v_fma_f32 v54, v14, v90, v54
	v_fma_f32 v55, v15, v90, v55
	v_mov_b32_e32 v56, v91
	v_fma_f32 v54, v42, v56, v54
	v_fma_f32 v55, v43, v56, v55
	ds_read_b128 v[84:87], v25 offset:432
	s_waitcnt lgkmcnt(10)
	v_fma_f32 v54, v8, v92, v54
	v_fma_f32 v55, v9, v92, v55
	v_fma_f32 v58, v40, v93, v54
	v_fma_f32 v59, v41, v93, v55
	v_fma_f32 v58, v10, v94, v58
	v_fma_f32 v59, v11, v94, v59
	v_mov_b32_e32 v60, v95
	v_fma_f32 v58, v38, v60, v58
	v_fma_f32 v59, v39, v60, v59
	s_waitcnt lgkmcnt(9)
	v_fma_f32 v58, v4, v96, v58
	v_fma_f32 v59, v5, v96, v59
	v_fma_f32 v54, v36, v97, v58
	v_fma_f32 v55, v37, v97, v59
	v_fma_f32 v54, v6, v98, v54
	v_fma_f32 v55, v7, v98, v55
	v_mov_b32_e32 v56, v99
	v_fma_f32 v54, v34, v56, v54
	v_fma_f32 v55, v35, v56, v55
	ds_read_b128 v[88:91], v25 offset:448
	s_waitcnt lgkmcnt(9)
	v_mov_b32_e32 v56, v103
	v_fma_f32 v54, v0, v100, v54
	v_fma_f32 v55, v1, v100, v55
	v_fma_f32 v54, v32, v101, v54
	v_fma_f32 v55, v33, v101, v55
	v_fma_f32 v54, v2, v102, v54
	v_fma_f32 v55, v3, v102, v55
	v_fma_f32 v54, v30, v56, v54
	v_fma_f32 v55, v31, v56, v55
	ds_read_b128 v[92:95], v25 offset:464
	v_fma_f32 v56, v22, v48, -v66
	v_fma_f32 v57, v23, v49, -v67
	v_fma_f32 v49, v23, v48, v67
	v_fma_f32 v48, v22, v48, v66
	v_mov_b32_e32 v57, v49
	v_add_f32_e64 v48, v56, v54
	v_add_f32_e64 v49, v57, v55
	v_mul_f32_e64 v66, v46, v49
	v_mul_f32_e64 v67, v47, v49
	ds_read_b128 v[96:99], v25 offset:480
	s_waitcnt lgkmcnt(10)
	v_fma_f32 v62, v12, v104, 0
	v_fma_f32 v63, v13, v104, 0
	v_fma_f32 v54, v44, v105, v62
	v_fma_f32 v55, v45, v105, v63
	v_fma_f32 v54, v14, v106, v54
	v_fma_f32 v55, v15, v106, v55
	v_mov_b32_e32 v56, v107
	v_fma_f32 v54, v42, v56, v54
	v_fma_f32 v55, v43, v56, v55
	ds_read_b128 v[100:103], v25 offset:496
	s_waitcnt lgkmcnt(10)
	v_fma_f32 v54, v8, v108, v54
	v_fma_f32 v55, v9, v108, v55
	v_fma_f32 v58, v40, v109, v54
	v_fma_f32 v59, v41, v109, v55
	v_fma_f32 v58, v10, v110, v58
	v_fma_f32 v59, v11, v110, v59
	v_mov_b32_e32 v60, v111
	v_fma_f32 v58, v38, v60, v58
	v_fma_f32 v59, v39, v60, v59
	s_waitcnt lgkmcnt(9)
	v_fma_f32 v58, v4, v112, v58
	v_fma_f32 v59, v5, v112, v59
	v_fma_f32 v54, v36, v113, v58
	v_fma_f32 v55, v37, v113, v59
	v_fma_f32 v54, v6, v114, v54
	v_fma_f32 v55, v7, v114, v55
	v_mov_b32_e32 v56, v115
	v_fma_f32 v54, v34, v56, v54
	v_fma_f32 v55, v35, v56, v55
	s_waitcnt lgkmcnt(8)
	v_mov_b32_e32 v56, v119
	v_fma_f32 v54, v0, v116, v54
	v_fma_f32 v55, v1, v116, v55
	v_fma_f32 v54, v32, v117, v54
	v_fma_f32 v55, v33, v117, v55
	v_fma_f32 v54, v2, v118, v54
	v_fma_f32 v55, v3, v118, v55
	v_fma_f32 v54, v30, v56, v54
	v_fma_f32 v55, v31, v56, v55
	v_fma_f32 v56, v22, v48, -v66
	v_fma_f32 v57, v23, v49, -v67
	v_fma_f32 v49, v23, v48, v67
	v_fma_f32 v48, v22, v48, v66
	v_mov_b32_e32 v57, v49
	v_add_f32_e64 v48, v56, v54
	v_add_f32_e64 v49, v57, v55
	v_mul_f32_e64 v66, v46, v49
	v_mul_f32_e64 v67, v47, v49
	s_waitcnt lgkmcnt(7)
	v_fma_f32 v62, v12, v72, 0
	v_fma_f32 v63, v13, v72, 0
	v_fma_f32 v54, v44, v73, v62
	v_fma_f32 v55, v45, v73, v63
	v_fma_f32 v54, v14, v74, v54
	v_fma_f32 v55, v15, v74, v55
	v_mov_b32_e32 v56, v75
	v_fma_f32 v54, v42, v56, v54
	v_fma_f32 v55, v43, v56, v55
	s_waitcnt lgkmcnt(6)
	v_fma_f32 v54, v8, v76, v54
	v_fma_f32 v55, v9, v76, v55
	v_fma_f32 v58, v40, v77, v54
	v_fma_f32 v59, v41, v77, v55
	v_fma_f32 v58, v10, v78, v58
	v_fma_f32 v59, v11, v78, v59
	v_mov_b32_e32 v60, v79
	v_fma_f32 v58, v38, v60, v58
	v_fma_f32 v59, v39, v60, v59
	s_waitcnt lgkmcnt(5)
	v_fma_f32 v58, v4, v80, v58
	v_fma_f32 v59, v5, v80, v59
	v_fma_f32 v54, v36, v81, v58
	v_fma_f32 v55, v37, v81, v59
	v_fma_f32 v54, v6, v82, v54
	v_fma_f32 v55, v7, v82, v55
	v_mov_b32_e32 v56, v83
	v_fma_f32 v54, v34, v56, v54
	v_fma_f32 v55, v35, v56, v55
	s_waitcnt lgkmcnt(4)
	v_mov_b32_e32 v56, v87
	v_fma_f32 v54, v0, v84, v54
	v_fma_f32 v55, v1, v84, v55
	v_fma_f32 v54, v32, v85, v54
	v_fma_f32 v55, v33, v85, v55
	v_fma_f32 v54, v2, v86, v54
	v_fma_f32 v55, v3, v86, v55
	v_fma_f32 v54, v30, v56, v54
	v_fma_f32 v55, v31, v56, v55
	v_fma_f32 v56, v22, v48, -v66
	v_fma_f32 v57, v23, v49, -v67
	v_fma_f32 v49, v23, v48, v67
	v_fma_f32 v48, v22, v48, v66
	v_mov_b32_e32 v57, v49
	v_add_f32_e64 v48, v56, v54
	v_add_f32_e64 v49, v57, v55
	v_mul_f32_e64 v66, v46, v49
	v_mul_f32_e64 v67, v47, v49
	s_waitcnt lgkmcnt(3)
	v_fma_f32 v62, v12, v88, 0
	v_fma_f32 v63, v13, v88, 0
	v_fma_f32 v54, v44, v89, v62
	v_fma_f32 v55, v45, v89, v63
	v_fma_f32 v54, v14, v90, v54
	v_fma_f32 v55, v15, v90, v55
	v_mov_b32_e32 v56, v91
	v_fma_f32 v54, v42, v56, v54
	v_fma_f32 v55, v43, v56, v55
	s_waitcnt lgkmcnt(2)
	v_fma_f32 v54, v8, v92, v54
	v_fma_f32 v55, v9, v92, v55
	v_fma_f32 v58, v40, v93, v54
	v_fma_f32 v59, v41, v93, v55
	v_fma_f32 v58, v10, v94, v58
	v_fma_f32 v59, v11, v94, v59
	v_mov_b32_e32 v60, v95
	v_fma_f32 v58, v38, v60, v58
	v_fma_f32 v59, v39, v60, v59
	s_waitcnt lgkmcnt(1)
	v_fma_f32 v58, v4, v96, v58
	v_fma_f32 v59, v5, v96, v59
	v_fma_f32 v54, v36, v97, v58
	v_fma_f32 v55, v37, v97, v59
	v_fma_f32 v54, v6, v98, v54
	v_fma_f32 v55, v7, v98, v55
	v_mov_b32_e32 v56, v99
	v_fma_f32 v54, v34, v56, v54
	v_fma_f32 v55, v35, v56, v55
	s_waitcnt lgkmcnt(0)
	v_mov_b32_e32 v56, v103
	v_fma_f32 v54, v0, v100, v54
	v_fma_f32 v55, v1, v100, v55
	v_fma_f32 v54, v32, v101, v54
	v_fma_f32 v55, v33, v101, v55
	v_fma_f32 v54, v2, v102, v54
	v_fma_f32 v55, v3, v102, v55
	v_fma_f32 v54, v30, v56, v54
	v_fma_f32 v55, v31, v56, v55
	v_fma_f32 v56, v22, v48, -v66
	v_fma_f32 v57, v23, v49, -v67
	v_fma_f32 v49, v23, v48, v67
	v_fma_f32 v48, v22, v48, v66
	v_mov_b32_e32 v57, v49
	v_add_f32_e64 v48, v56, v54
	v_add_f32_e64 v49, v57, v55
	s_cbranch_scc1 .LBB0_588
; #define LAS __attribute__((address_space(3)))
; DI float lo16(unsigned u) { return __uint_as_float(u << 16); }
; DI float hi16(unsigned u) { return __uint_as_float(u & 0xffff0000u); }
; DI float gelu_tanh(float x) { float u = 0.7978845608028654f * (x + 0.044715f * x * x * x); float e = __expf(2.f * u); float th = 1.f - 2.f / (e + 1.f); return 0.5f * x * (1.f + th); }
; DI void lds_wait() { asm volatile("s_waitcnt lgkmcnt(0)" ::: "memory"); }
; template <bool PASSB>
; DI void s5_pass(const int tid, LAS unsigned char* lds, const P& p, int G, int c0) {
;     ...
;         for (int tile = 0; tile < 16; ++tile) {
;             if (lane < 32) { const int tk = lane >> 1, hf = lane & 1;
;                 const u32x4 raw = *(const u32x4*)(us5 + (tokbase + tile * 16 + tk) * 256 + g * 16 + hf * 8);
;                 LAS float* d = ubuf + tk * 16 + hf * 8;
;                 *(LAS f32x4*)d = (f32x4){lo16(raw.x), hi16(raw.x), lo16(raw.y), hi16(raw.y)}; *(LAS f32x4*)(d + 4) = (f32x4){lo16(raw.z), hi16(raw.z), lo16(raw.w), hi16(raw.w)}; }
;             lds_wait();
; #pragma unroll 8
;             for (int t = 0; t < 16; ++t) {
;                 float bur = 0.f, bui = 0.f;
; #pragma unroll
;                 for (int k = 0; k < 4; ++k) { const f32x4 u = *(const LAS f32x4*)(ubuf + t * 16 + k * 4);
; #pragma unroll
;                     for (int e = 0; e < 4; ++e) { bur += bre[4 * k + e] * u[e]; bui += bim[4 * k + e] * u[e]; } }
;                 const float nr = are * hre - aim * him + bur, ni = are * him + aim * hre + bui; hre = nr; him = ni;
;                 if (PASSB) { hbuf[t * 136 + lane] = f2bf(hre); hbuf[t * 136 + 64 + lane] = f2bf(-him); }
;             }
;             if (PASSB) {
;                 lds_wait();
;                 f32x4 acc = (f32x4){0.f, 0.f, 0.f, 0.f};
; #pragma unroll
;                 for (int ks = 0; ks < 4; ++ks) { const bf16x8 a = *(const LAS bf16x8*)(hbuf + fr * 136 + ks * 32 + fq * 8); acc = mfma16(a, cf[ks], acc); }
; #pragma unroll
;                 for (int j = 0; j < 4; ++j) { const int tk = fq * 4 + j; const float y = acc[j] + dsk * ubuf[tk * 16 + fr];
;                     zs5[(tokbase + tile * 16 + tk) * 256 + g * 16 + fr] = f2bf(gelu_tanh(y)); }
;             }
;             lds_wait();
;         }
;         if (!PASSB) { float* he = hend + (((size_t)(b * 16 + g) * 8 + seg) * 64 + lane) * 2; he[0] = hre; he[1] = him; }
	s_waitcnt lgkmcnt(0)
	s_add_i32 s6, s6, 1
	s_cmp_eq_u32 s6, 16
	s_cbranch_scc0 .LBB0_585
	v_lshl_add_u32 v0, v24, 4, s5
	v_ashrrev_i32_e32 v1, 31, v0
	v_readlane_b32 s0, v253, 16
	v_lshlrev_b64 v[0:1], 12, v[0:1]
	s_add_i32 s4, s4, s0
	v_lshl_add_u64 v[0:1], v[20:21], 0, v[0:1]
	s_cmpk_gt_i32 s4, 0x1ff
	v_readlane_b32 s1, v253, 17
	global_store_dwordx2 v[0:1], v[48:49], off
	s_cbranch_scc0 .LBB0_584
